# XLN epilogues (P4, P6): cache-line prefetch of the residual tile rows ahead of the serialized group loads
# baseline (speedup 1.0000x reference)
.LBB0_820:
	v_mov_b32_e32 v134, v221
	v_mov_b32_e32 v135, v220
	s_lshl_b32 s6, s73, 8
	v_add_u32_e32 v214, s63, v135
	s_lshl_b32 s0, s76, 8
	v_add_u32_e32 v130, s6, v214
	s_or_b32 s0, s0, s64
	v_lshl_add_u32 v174, v134, 3, s0
	v_ashrrev_i32_e32 v131, 31, v130
	v_ashrrev_i32_e32 v175, 31, v174
	v_lshlrev_b64 v[132:133], 13, v[130:131]
	v_lshl_add_u64 v[136:137], s[10:11], 0, v[132:133]
	v_lshlrev_b64 v[132:133], 1, v[174:175]
	v_lshl_add_u64 v[176:177], v[136:137], 0, v[132:133]
	global_load_dwordx4 v[136:139], v[176:177], off
	v_readlane_b32 s0, v254, 58
	v_lshlrev_b64 v[188:189], 12, v[130:131]
	v_readlane_b32 s1, v254, 59
	s_waitcnt vmcnt(0)
	v_lshrrev_b32_e32 v131, 23, v136
	v_lshl_add_u64 v[140:141], s[0:1], 0, v[188:189]
	v_lshl_add_u64 v[144:145], v[140:141], 0, v[174:175]
	s_mov_b32 s99, 0
	s_mov_b32 s98, 0x20000
	v_lshl_add_u64 v[242:243], v[176:177], 0, s[98:99]
	global_load_dword v244, v[242:243], off
	global_load_dword v245, v[242:243], off offset:256
	s_mov_b32 s98, 0x10000
	v_lshl_add_u64 v[242:243], v[144:145], 0, s[98:99]
	global_load_dword v246, v[242:243], off
	global_load_dword v247, v[242:243], off offset:128
	s_mov_b32 s98, 0x40000
	v_lshl_add_u64 v[242:243], v[176:177], 0, s[98:99]
	global_load_dword v244, v[242:243], off
	global_load_dword v245, v[242:243], off offset:256
	s_mov_b32 s98, 0x20000
	v_lshl_add_u64 v[242:243], v[144:145], 0, s[98:99]
	global_load_dword v246, v[242:243], off
	global_load_dword v247, v[242:243], off offset:128
	s_mov_b32 s98, 0x60000
	v_lshl_add_u64 v[242:243], v[176:177], 0, s[98:99]
	global_load_dword v244, v[242:243], off
	global_load_dword v245, v[242:243], off offset:256
	s_mov_b32 s98, 0x30000
	v_lshl_add_u64 v[242:243], v[144:145], 0, s[98:99]
	global_load_dword v246, v[242:243], off
	global_load_dword v247, v[242:243], off offset:128
	s_mov_b32 s98, 0x100000
	v_lshl_add_u64 v[242:243], v[176:177], 0, s[98:99]
	global_load_dword v244, v[242:243], off
	global_load_dword v245, v[242:243], off offset:256
	s_mov_b32 s98, 0x80000
	v_lshl_add_u64 v[242:243], v[144:145], 0, s[98:99]
	global_load_dword v246, v[242:243], off
	global_load_dword v247, v[242:243], off offset:128
	s_mov_b32 s98, 0x120000
	v_lshl_add_u64 v[242:243], v[176:177], 0, s[98:99]
	global_load_dword v244, v[242:243], off
	global_load_dword v245, v[242:243], off offset:256
	s_mov_b32 s98, 0x90000
	v_lshl_add_u64 v[242:243], v[144:145], 0, s[98:99]
	global_load_dword v246, v[242:243], off
	global_load_dword v247, v[242:243], off offset:128
	s_mov_b32 s98, 0x140000
	v_lshl_add_u64 v[242:243], v[176:177], 0, s[98:99]
	global_load_dword v244, v[242:243], off
	global_load_dword v245, v[242:243], off offset:256
	s_mov_b32 s98, 0xa0000
	v_lshl_add_u64 v[242:243], v[144:145], 0, s[98:99]
	global_load_dword v246, v[242:243], off
	global_load_dword v247, v[242:243], off offset:128
	s_mov_b32 s98, 0x160000
	v_lshl_add_u64 v[242:243], v[176:177], 0, s[98:99]
	global_load_dword v244, v[242:243], off
	global_load_dword v245, v[242:243], off offset:256
	s_mov_b32 s98, 0xb0000
	v_lshl_add_u64 v[242:243], v[144:145], 0, s[98:99]
	global_load_dword v246, v[242:243], off
	global_load_dword v247, v[242:243], off offset:128
	global_load_dwordx2 v[146:147], v[144:145], off
	global_load_dwordx4 v[140:143], v[176:177], off offset:256
	s_nop 0
	global_load_dwordx2 v[144:145], v[144:145], off offset:128
	v_bfe_u32 v178, v136, 7, 9
	v_lshrrev_b32_e32 v179, 23, v138
	v_and_b32_e32 v131, 0xff, v131
	v_and_b32_e32 v187, 0xff, v178
	v_bfe_u32 v180, v138, 7, 9
	v_and_b32_e32 v190, 0xff, v179
	v_lshl_add_u32 v179, v131, 23, v233
	v_lshl_add_u32 v178, v187, 23, v233
	v_lshrrev_b32_e32 v181, 23, v137
	v_and_b32_e32 v191, 0xff, v180
	v_pk_mul_f32 v[178:179], v[178:179], s[34:35] op_sel_hi:[1,0]
	v_cmp_lt_u32_e32 vcc, 15, v131
	v_bfe_u32 v182, v137, 7, 9
	v_and_b32_e32 v192, 0xff, v181
	v_lshl_add_u32 v181, v190, 23, v233
	v_lshl_add_u32 v180, v191, 23, v233
	v_cndmask_b32_e32 v179, 0, v179, vcc
	v_cmp_lt_u32_e32 vcc, 15, v187
	v_lshrrev_b32_e32 v183, 23, v139
	v_and_b32_e32 v193, 0xff, v182
	v_pk_mul_f32 v[180:181], v[180:181], s[34:35] op_sel_hi:[1,0]
	v_cndmask_b32_e32 v178, 0, v178, vcc
	v_cmp_lt_u32_e32 vcc, 15, v190
	v_bfe_u32 v184, v139, 7, 9
	v_and_b32_e32 v194, 0xff, v183
	v_lshl_add_u32 v183, v192, 23, v233
	v_lshl_add_u32 v182, v193, 23, v233
	v_cndmask_b32_e32 v181, 0, v181, vcc
	v_cmp_lt_u32_e32 vcc, 15, v191
	v_and_b32_e32 v195, 0xff, v184
	v_pk_mul_f32 v[182:183], v[182:183], s[34:35] op_sel_hi:[1,0]
	v_cndmask_b32_e32 v180, 0, v180, vcc
	v_cmp_lt_u32_e32 vcc, 15, v192
	v_lshl_add_u32 v185, v194, 23, v233
	v_lshl_add_u32 v184, v195, 23, v233
	v_cndmask_b32_e32 v183, 0, v183, vcc
	v_cmp_lt_u32_e32 vcc, 15, v193
	v_pk_mul_f32 v[184:185], v[184:185], s[34:35] op_sel_hi:[1,0]
	v_lshlrev_b32_e32 v148, 16, v136
	v_cndmask_b32_e32 v182, 0, v182, vcc
	v_cmp_lt_u32_e32 vcc, 15, v194
	v_and_b32_e32 v149, 0xffff0000, v136
	v_lshlrev_b32_e32 v156, 16, v137
	v_cndmask_b32_e32 v185, 0, v185, vcc
	v_cmp_lt_u32_e32 vcc, 15, v195
	v_and_b32_e32 v157, 0xffff0000, v137
	v_lshlrev_b32_e32 v136, 16, v139
	v_and_b32_e32 v137, 0xffff0000, v139
	v_cndmask_b32_e32 v184, 0, v184, vcc
	v_lshlrev_b32_e32 v152, 16, v138
	v_and_b32_e32 v153, 0xffff0000, v138
	s_waitcnt vmcnt(2)
	v_cvt_f32_i32_sdwa v161, sext(v147) dst_sel:DWORD dst_unused:UNUSED_PAD src0_sel:BYTE_3
	v_cvt_f32_i32_sdwa v160, sext(v147) dst_sel:DWORD dst_unused:UNUSED_PAD src0_sel:BYTE_2
	s_waitcnt vmcnt(1)
	v_lshrrev_b32_e32 v186, 23, v140
	v_bfe_u32 v131, v140, 7, 9
	v_cvt_f32_i32_sdwa v151, sext(v146) dst_sel:DWORD dst_unused:UNUSED_PAD src0_sel:BYTE_1
	v_cvt_f32_i32_sdwa v150, sext(v146) dst_sel:DWORD dst_unused:UNUSED_PAD src0_sel:BYTE_0
	v_lshlrev_b32_e32 v138, 16, v140
	v_and_b32_e32 v139, 0xffff0000, v140
	v_pk_fma_f32 v[136:137], v[184:185], v[160:161], v[136:137]
	v_and_b32_e32 v140, 0xff, v186
	v_and_b32_e32 v131, 0xff, v131
	v_cvt_f32_i32_sdwa v155, sext(v147) dst_sel:DWORD dst_unused:UNUSED_PAD src0_sel:BYTE_1
	v_cvt_f32_i32_sdwa v154, sext(v147) dst_sel:DWORD dst_unused:UNUSED_PAD src0_sel:BYTE_0
	v_cvt_f32_i32_sdwa v159, sext(v146) dst_sel:DWORD dst_unused:UNUSED_PAD src0_sel:BYTE_3
	v_cvt_f32_i32_sdwa v158, sext(v146) dst_sel:DWORD dst_unused:UNUSED_PAD src0_sel:BYTE_2
	s_waitcnt vmcnt(0)
	v_cvt_f32_i32_sdwa v147, sext(v144) dst_sel:DWORD dst_unused:UNUSED_PAD src0_sel:BYTE_1
	v_cvt_f32_i32_sdwa v146, sext(v144) dst_sel:DWORD dst_unused:UNUSED_PAD src0_sel:BYTE_0
	v_pk_fma_f32 v[12:13], v[136:137], s[82:83], v[12:13] op_sel_hi:[1,0,1]
	v_lshl_add_u32 v137, v140, 23, v233
	v_lshl_add_u32 v136, v131, 23, v233
	v_pk_mul_f32 v[136:137], v[136:137], s[34:35] op_sel_hi:[1,0]
	v_cmp_lt_u32_e32 vcc, 15, v140
	v_bfe_u32 v140, v142, 7, 9
	v_pk_fma_f32 v[148:149], v[178:179], v[150:151], v[148:149]
	v_cndmask_b32_e32 v137, 0, v137, vcc
	v_cmp_lt_u32_e32 vcc, 15, v131
	v_lshrrev_b32_e32 v131, 23, v142
	v_and_b32_e32 v131, 0xff, v131
	v_cndmask_b32_e32 v136, 0, v136, vcc
	v_and_b32_e32 v140, 0xff, v140
	v_pk_fma_f32 v[14:15], v[148:149], s[82:83], v[14:15] op_sel_hi:[1,0,1]
	v_pk_fma_f32 v[136:137], v[136:137], v[146:147], v[138:139]
	v_cvt_f32_i32_sdwa v147, sext(v145) dst_sel:DWORD dst_unused:UNUSED_PAD src0_sel:BYTE_1
	v_cvt_f32_i32_sdwa v146, sext(v145) dst_sel:DWORD dst_unused:UNUSED_PAD src0_sel:BYTE_0
	v_lshl_add_u32 v149, v131, 23, v233
	v_lshl_add_u32 v148, v140, 23, v233
	v_pk_mul_f32 v[148:149], v[148:149], s[34:35] op_sel_hi:[1,0]
	v_cmp_lt_u32_e32 vcc, 15, v131
	v_lshrrev_b32_e32 v131, 23, v141
	v_lshlrev_b32_e32 v138, 16, v142
	v_cndmask_b32_e32 v149, 0, v149, vcc
	v_cmp_lt_u32_e32 vcc, 15, v140
	v_bfe_u32 v140, v141, 7, 9
	v_and_b32_e32 v139, 0xffff0000, v142
	v_cndmask_b32_e32 v148, 0, v148, vcc
	v_and_b32_e32 v131, 0xff, v131
	v_and_b32_e32 v142, 0xff, v140
	v_pk_fma_f32 v[138:139], v[148:149], v[146:147], v[138:139]
	v_lshlrev_b32_e32 v146, 16, v141
	v_and_b32_e32 v147, 0xffff0000, v141
	v_cvt_f32_i32_sdwa v149, sext(v144) dst_sel:DWORD dst_unused:UNUSED_PAD src0_sel:BYTE_3
	v_cvt_f32_i32_sdwa v148, sext(v144) dst_sel:DWORD dst_unused:UNUSED_PAD src0_sel:BYTE_2
	v_lshl_add_u32 v141, v131, 23, v233
	v_lshl_add_u32 v140, v142, 23, v233
	v_pk_mul_f32 v[140:141], v[140:141], s[34:35] op_sel_hi:[1,0]
	v_cmp_lt_u32_e32 vcc, 15, v131
	v_lshrrev_b32_e32 v131, 23, v143
	v_and_b32_e32 v131, 0xff, v131
	v_cndmask_b32_e32 v141, 0, v141, vcc
	v_cmp_lt_u32_e32 vcc, 15, v142
	v_bfe_u32 v142, v143, 7, 9
	v_and_b32_e32 v144, 0xff, v142
	v_cndmask_b32_e32 v140, 0, v140, vcc
	v_pk_fma_f32 v[140:141], v[140:141], v[148:149], v[146:147]
	v_lshlrev_b32_e32 v146, 16, v143
	v_and_b32_e32 v147, 0xffff0000, v143
	v_cvt_f32_i32_sdwa v149, sext(v145) dst_sel:DWORD dst_unused:UNUSED_PAD src0_sel:BYTE_3
	v_cvt_f32_i32_sdwa v148, sext(v145) dst_sel:DWORD dst_unused:UNUSED_PAD src0_sel:BYTE_2
	v_lshl_add_u32 v143, v131, 23, v233
	v_lshl_add_u32 v142, v144, 23, v233
	v_pk_mul_f32 v[142:143], v[142:143], s[34:35] op_sel_hi:[1,0]
	v_cmp_lt_u32_e32 vcc, 15, v131
	v_pk_fma_f32 v[8:9], v[140:141], s[82:83], v[8:9] op_sel_hi:[1,0,1]
	v_add_u32_e32 v140, 16, v130
	v_cndmask_b32_e32 v143, 0, v143, vcc
	v_cmp_lt_u32_e32 vcc, 15, v144
	v_ashrrev_i32_e32 v141, 31, v140
	v_pk_fma_f32 v[6:7], v[136:137], s[82:83], v[6:7] op_sel_hi:[1,0,1]
	v_cndmask_b32_e32 v142, 0, v142, vcc
	v_lshlrev_b64 v[136:137], 13, v[140:141]
	v_pk_fma_f32 v[150:151], v[180:181], v[154:155], v[152:153]
	v_pk_fma_f32 v[152:153], v[182:183], v[158:159], v[156:157]
	v_pk_fma_f32 v[142:143], v[142:143], v[148:149], v[146:147]
	v_lshl_add_u64 v[136:137], s[10:11], 0, v[136:137]
	v_pk_fma_f32 v[16:17], v[152:153], s[82:83], v[16:17] op_sel_hi:[1,0,1]
	v_pk_fma_f32 v[10:11], v[150:151], s[82:83], v[10:11] op_sel_hi:[1,0,1]
	v_pk_fma_f32 v[4:5], v[142:143], s[82:83], v[4:5] op_sel_hi:[1,0,1]
	v_pk_fma_f32 v[2:3], v[138:139], s[82:83], v[2:3] op_sel_hi:[1,0,1]
	v_lshl_add_u64 v[178:179], v[136:137], 0, v[132:133]
	global_load_dwordx4 v[136:139], v[178:179], off
	v_lshlrev_b64 v[186:187], 12, v[140:141]
	v_lshl_add_u64 v[140:141], s[0:1], 0, v[186:187]
	v_lshl_add_u64 v[144:145], v[140:141], 0, v[174:175]
	global_load_dwordx2 v[146:147], v[144:145], off
	global_load_dwordx4 v[140:143], v[178:179], off offset:256
	s_nop 0
	global_load_dwordx2 v[144:145], v[144:145], off offset:128
	s_waitcnt vmcnt(3)
	v_lshlrev_b32_e32 v148, 16, v136
	v_and_b32_e32 v149, 0xffff0000, v136
	v_lshrrev_b32_e32 v131, 23, v136
	v_bfe_u32 v136, v136, 7, 9
	v_and_b32_e32 v131, 0xff, v131
	v_and_b32_e32 v136, 0xff, v136
	s_waitcnt vmcnt(2)
	v_cvt_f32_i32_sdwa v151, sext(v146) dst_sel:DWORD dst_unused:UNUSED_PAD src0_sel:BYTE_1
	v_cvt_f32_i32_sdwa v150, sext(v146) dst_sel:DWORD dst_unused:UNUSED_PAD src0_sel:BYTE_0
	v_lshl_add_u32 v153, v131, 23, v233
	v_lshl_add_u32 v152, v136, 23, v233
	v_pk_mul_f32 v[152:153], v[152:153], s[34:35] op_sel_hi:[1,0]
	v_cmp_lt_u32_e32 vcc, 15, v131
	v_lshrrev_b32_e32 v131, 23, v138
	v_and_b32_e32 v131, 0xff, v131
	v_cndmask_b32_e32 v153, 0, v153, vcc
	v_cmp_lt_u32_e32 vcc, 15, v136
	v_bfe_u32 v136, v138, 7, 9
	v_and_b32_e32 v136, 0xff, v136
	v_cndmask_b32_e32 v152, 0, v152, vcc
	v_pk_fma_f32 v[148:149], v[152:153], v[150:151], v[148:149]
	v_cvt_f32_i32_sdwa v153, sext(v147) dst_sel:DWORD dst_unused:UNUSED_PAD src0_sel:BYTE_1
	v_cvt_f32_i32_sdwa v152, sext(v147) dst_sel:DWORD dst_unused:UNUSED_PAD src0_sel:BYTE_0
	v_lshl_add_u32 v155, v131, 23, v233
	v_lshl_add_u32 v154, v136, 23, v233
	v_pk_mul_f32 v[154:155], v[154:155], s[34:35] op_sel_hi:[1,0]
	v_cmp_lt_u32_e32 vcc, 15, v131
	v_lshrrev_b32_e32 v131, 23, v137
	v_lshlrev_b32_e32 v150, 16, v138
	v_cndmask_b32_e32 v155, 0, v155, vcc
	v_cmp_lt_u32_e32 vcc, 15, v136
	v_bfe_u32 v136, v137, 7, 9
	v_and_b32_e32 v151, 0xffff0000, v138
	v_cndmask_b32_e32 v154, 0, v154, vcc
	v_and_b32_e32 v131, 0xff, v131
	v_and_b32_e32 v138, 0xff, v136
	v_pk_fma_f32 v[150:151], v[154:155], v[152:153], v[150:151]
	v_lshlrev_b32_e32 v152, 16, v137
	v_and_b32_e32 v153, 0xffff0000, v137
	v_cvt_f32_i32_sdwa v155, sext(v146) dst_sel:DWORD dst_unused:UNUSED_PAD src0_sel:BYTE_3
	v_cvt_f32_i32_sdwa v154, sext(v146) dst_sel:DWORD dst_unused:UNUSED_PAD src0_sel:BYTE_2
	v_lshl_add_u32 v137, v131, 23, v233
	v_lshl_add_u32 v136, v138, 23, v233
	v_pk_mul_f32 v[136:137], v[136:137], s[34:35] op_sel_hi:[1,0]
	v_cmp_lt_u32_e32 vcc, 15, v131
	v_lshrrev_b32_e32 v131, 23, v139
	v_and_b32_e32 v131, 0xff, v131
	v_cndmask_b32_e32 v137, 0, v137, vcc
	v_cmp_lt_u32_e32 vcc, 15, v138
	v_bfe_u32 v138, v139, 7, 9
	v_and_b32_e32 v146, 0xff, v138
	v_cndmask_b32_e32 v136, 0, v136, vcc
	v_pk_fma_f32 v[136:137], v[136:137], v[154:155], v[152:153]
	v_lshlrev_b32_e32 v152, 16, v139
	v_and_b32_e32 v153, 0xffff0000, v139
	v_cvt_f32_i32_sdwa v155, sext(v147) dst_sel:DWORD dst_unused:UNUSED_PAD src0_sel:BYTE_3
	v_cvt_f32_i32_sdwa v154, sext(v147) dst_sel:DWORD dst_unused:UNUSED_PAD src0_sel:BYTE_2
	v_lshl_add_u32 v139, v131, 23, v233
	v_lshl_add_u32 v138, v146, 23, v233
	v_pk_mul_f32 v[138:139], v[138:139], s[34:35] op_sel_hi:[1,0]
	v_cmp_lt_u32_e32 vcc, 15, v131
	v_pk_fma_f32 v[36:37], v[136:137], s[82:83], v[36:37] op_sel_hi:[1,0,1]
	s_waitcnt vmcnt(1)
	v_lshlrev_b32_e32 v136, 16, v140
	v_cndmask_b32_e32 v139, 0, v139, vcc
	v_cmp_lt_u32_e32 vcc, 15, v146
	v_and_b32_e32 v137, 0xffff0000, v140
	v_lshrrev_b32_e32 v131, 23, v140
	v_cndmask_b32_e32 v138, 0, v138, vcc
	v_bfe_u32 v140, v140, 7, 9
	v_pk_fma_f32 v[138:139], v[138:139], v[154:155], v[152:153]
	v_and_b32_e32 v131, 0xff, v131
	v_and_b32_e32 v140, 0xff, v140
	v_pk_fma_f32 v[28:29], v[138:139], s[82:83], v[28:29] op_sel_hi:[1,0,1]
	s_waitcnt vmcnt(0)
	v_cvt_f32_i32_sdwa v139, sext(v144) dst_sel:DWORD dst_unused:UNUSED_PAD src0_sel:BYTE_1
	v_cvt_f32_i32_sdwa v138, sext(v144) dst_sel:DWORD dst_unused:UNUSED_PAD src0_sel:BYTE_0
	v_lshl_add_u32 v147, v131, 23, v233
	v_lshl_add_u32 v146, v140, 23, v233
	v_pk_mul_f32 v[146:147], v[146:147], s[34:35] op_sel_hi:[1,0]
	v_cmp_lt_u32_e32 vcc, 15, v131
	v_lshrrev_b32_e32 v131, 23, v142
	v_and_b32_e32 v131, 0xff, v131
	v_cndmask_b32_e32 v147, 0, v147, vcc
	v_cmp_lt_u32_e32 vcc, 15, v140
	v_bfe_u32 v140, v142, 7, 9
	v_and_b32_e32 v140, 0xff, v140
	v_cndmask_b32_e32 v146, 0, v146, vcc
	v_pk_fma_f32 v[34:35], v[148:149], s[82:83], v[34:35] op_sel_hi:[1,0,1]
	v_pk_fma_f32 v[136:137], v[146:147], v[138:139], v[136:137]
	v_cvt_f32_i32_sdwa v147, sext(v145) dst_sel:DWORD dst_unused:UNUSED_PAD src0_sel:BYTE_1
	v_cvt_f32_i32_sdwa v146, sext(v145) dst_sel:DWORD dst_unused:UNUSED_PAD src0_sel:BYTE_0
	v_lshl_add_u32 v149, v131, 23, v233
	v_lshl_add_u32 v148, v140, 23, v233
	v_pk_mul_f32 v[148:149], v[148:149], s[34:35] op_sel_hi:[1,0]
	v_cmp_lt_u32_e32 vcc, 15, v131
	v_lshrrev_b32_e32 v131, 23, v141
	v_lshlrev_b32_e32 v138, 16, v142
	v_cndmask_b32_e32 v149, 0, v149, vcc
	v_cmp_lt_u32_e32 vcc, 15, v140
	v_bfe_u32 v140, v141, 7, 9
	v_and_b32_e32 v139, 0xffff0000, v142
	v_cndmask_b32_e32 v148, 0, v148, vcc
	v_and_b32_e32 v131, 0xff, v131
	v_and_b32_e32 v142, 0xff, v140
	v_pk_fma_f32 v[138:139], v[148:149], v[146:147], v[138:139]
	v_lshlrev_b32_e32 v146, 16, v141
	v_and_b32_e32 v147, 0xffff0000, v141
	v_cvt_f32_i32_sdwa v149, sext(v144) dst_sel:DWORD dst_unused:UNUSED_PAD src0_sel:BYTE_3
	v_cvt_f32_i32_sdwa v148, sext(v144) dst_sel:DWORD dst_unused:UNUSED_PAD src0_sel:BYTE_2
	v_lshl_add_u32 v141, v131, 23, v233
	v_lshl_add_u32 v140, v142, 23, v233
	v_pk_mul_f32 v[140:141], v[140:141], s[34:35] op_sel_hi:[1,0]
	v_cmp_lt_u32_e32 vcc, 15, v131
	v_lshrrev_b32_e32 v131, 23, v143
	v_and_b32_e32 v131, 0xff, v131
	v_cndmask_b32_e32 v141, 0, v141, vcc
	v_cmp_lt_u32_e32 vcc, 15, v142
	v_bfe_u32 v142, v143, 7, 9
	v_and_b32_e32 v144, 0xff, v142
	v_cndmask_b32_e32 v140, 0, v140, vcc
	v_pk_fma_f32 v[140:141], v[140:141], v[148:149], v[146:147]
	v_lshlrev_b32_e32 v146, 16, v143
	v_and_b32_e32 v147, 0xffff0000, v143
	v_cvt_f32_i32_sdwa v149, sext(v145) dst_sel:DWORD dst_unused:UNUSED_PAD src0_sel:BYTE_3
	v_cvt_f32_i32_sdwa v148, sext(v145) dst_sel:DWORD dst_unused:UNUSED_PAD src0_sel:BYTE_2
	v_lshl_add_u32 v143, v131, 23, v233
	v_lshl_add_u32 v142, v144, 23, v233
	v_pk_mul_f32 v[142:143], v[142:143], s[34:35] op_sel_hi:[1,0]
	v_cmp_lt_u32_e32 vcc, 15, v131
	v_pk_fma_f32 v[24:25], v[140:141], s[82:83], v[24:25] op_sel_hi:[1,0,1]
	v_add_u32_e32 v140, 32, v130
	v_cndmask_b32_e32 v143, 0, v143, vcc
	v_cmp_lt_u32_e32 vcc, 15, v144
	v_ashrrev_i32_e32 v141, 31, v140
	v_pk_fma_f32 v[22:23], v[136:137], s[82:83], v[22:23] op_sel_hi:[1,0,1]
	v_cndmask_b32_e32 v142, 0, v142, vcc
	v_lshlrev_b64 v[136:137], 13, v[140:141]
	v_pk_fma_f32 v[142:143], v[142:143], v[148:149], v[146:147]
	v_lshl_add_u64 v[136:137], s[10:11], 0, v[136:137]
	v_pk_fma_f32 v[26:27], v[150:151], s[82:83], v[26:27] op_sel_hi:[1,0,1]
	v_pk_fma_f32 v[20:21], v[142:143], s[82:83], v[20:21] op_sel_hi:[1,0,1]
	v_pk_fma_f32 v[18:19], v[138:139], s[82:83], v[18:19] op_sel_hi:[1,0,1]
	v_lshl_add_u64 v[180:181], v[136:137], 0, v[132:133]
	global_load_dwordx4 v[136:139], v[180:181], off
	v_lshlrev_b64 v[190:191], 12, v[140:141]
	v_lshl_add_u64 v[140:141], s[0:1], 0, v[190:191]
	v_lshl_add_u64 v[144:145], v[140:141], 0, v[174:175]
	global_load_dwordx2 v[146:147], v[144:145], off
	global_load_dwordx4 v[140:143], v[180:181], off offset:256
	s_nop 0
	global_load_dwordx2 v[144:145], v[144:145], off offset:128
	s_waitcnt vmcnt(3)
	v_lshlrev_b32_e32 v148, 16, v136
	v_and_b32_e32 v149, 0xffff0000, v136
	v_lshrrev_b32_e32 v131, 23, v136
	v_bfe_u32 v136, v136, 7, 9
	v_and_b32_e32 v131, 0xff, v131
	v_and_b32_e32 v136, 0xff, v136
	s_waitcnt vmcnt(2)
	v_cvt_f32_i32_sdwa v151, sext(v146) dst_sel:DWORD dst_unused:UNUSED_PAD src0_sel:BYTE_1
	v_cvt_f32_i32_sdwa v150, sext(v146) dst_sel:DWORD dst_unused:UNUSED_PAD src0_sel:BYTE_0
	v_lshl_add_u32 v153, v131, 23, v233
	v_lshl_add_u32 v152, v136, 23, v233
	v_pk_mul_f32 v[152:153], v[152:153], s[34:35] op_sel_hi:[1,0]
	v_cmp_lt_u32_e32 vcc, 15, v131
	v_lshrrev_b32_e32 v131, 23, v138
	v_and_b32_e32 v131, 0xff, v131
	v_cndmask_b32_e32 v153, 0, v153, vcc
	v_cmp_lt_u32_e32 vcc, 15, v136
	v_bfe_u32 v136, v138, 7, 9
	v_and_b32_e32 v136, 0xff, v136
	v_cndmask_b32_e32 v152, 0, v152, vcc
	v_pk_fma_f32 v[148:149], v[152:153], v[150:151], v[148:149]
	v_cvt_f32_i32_sdwa v153, sext(v147) dst_sel:DWORD dst_unused:UNUSED_PAD src0_sel:BYTE_1
	v_cvt_f32_i32_sdwa v152, sext(v147) dst_sel:DWORD dst_unused:UNUSED_PAD src0_sel:BYTE_0
	v_lshl_add_u32 v155, v131, 23, v233
	v_lshl_add_u32 v154, v136, 23, v233
	v_pk_mul_f32 v[154:155], v[154:155], s[34:35] op_sel_hi:[1,0]
	v_cmp_lt_u32_e32 vcc, 15, v131
	v_lshrrev_b32_e32 v131, 23, v137
	v_lshlrev_b32_e32 v150, 16, v138
	v_cndmask_b32_e32 v155, 0, v155, vcc
	v_cmp_lt_u32_e32 vcc, 15, v136
	v_bfe_u32 v136, v137, 7, 9
	v_and_b32_e32 v151, 0xffff0000, v138
	v_cndmask_b32_e32 v154, 0, v154, vcc
	v_and_b32_e32 v131, 0xff, v131
	v_and_b32_e32 v138, 0xff, v136
	v_pk_fma_f32 v[150:151], v[154:155], v[152:153], v[150:151]
	v_lshlrev_b32_e32 v152, 16, v137
	v_and_b32_e32 v153, 0xffff0000, v137
	v_cvt_f32_i32_sdwa v155, sext(v146) dst_sel:DWORD dst_unused:UNUSED_PAD src0_sel:BYTE_3
	v_cvt_f32_i32_sdwa v154, sext(v146) dst_sel:DWORD dst_unused:UNUSED_PAD src0_sel:BYTE_2
	v_lshl_add_u32 v137, v131, 23, v233
	v_lshl_add_u32 v136, v138, 23, v233
	v_pk_mul_f32 v[136:137], v[136:137], s[34:35] op_sel_hi:[1,0]
	v_cmp_lt_u32_e32 vcc, 15, v131
	v_lshrrev_b32_e32 v131, 23, v139
	v_and_b32_e32 v131, 0xff, v131
	v_cndmask_b32_e32 v137, 0, v137, vcc
	v_cmp_lt_u32_e32 vcc, 15, v138
	v_bfe_u32 v138, v139, 7, 9
	v_and_b32_e32 v146, 0xff, v138
	v_cndmask_b32_e32 v136, 0, v136, vcc
	v_pk_fma_f32 v[136:137], v[136:137], v[154:155], v[152:153]
	v_lshlrev_b32_e32 v152, 16, v139
	v_and_b32_e32 v153, 0xffff0000, v139
	v_cvt_f32_i32_sdwa v155, sext(v147) dst_sel:DWORD dst_unused:UNUSED_PAD src0_sel:BYTE_3
	v_cvt_f32_i32_sdwa v154, sext(v147) dst_sel:DWORD dst_unused:UNUSED_PAD src0_sel:BYTE_2
	v_lshl_add_u32 v139, v131, 23, v233
	v_lshl_add_u32 v138, v146, 23, v233
	v_pk_mul_f32 v[138:139], v[138:139], s[34:35] op_sel_hi:[1,0]
	v_cmp_lt_u32_e32 vcc, 15, v131
	v_pk_fma_f32 v[48:49], v[136:137], s[82:83], v[48:49] op_sel_hi:[1,0,1]
	s_waitcnt vmcnt(1)
	v_lshlrev_b32_e32 v136, 16, v140
	v_cndmask_b32_e32 v139, 0, v139, vcc
	v_cmp_lt_u32_e32 vcc, 15, v146
	v_and_b32_e32 v137, 0xffff0000, v140
	v_lshrrev_b32_e32 v131, 23, v140
	v_cndmask_b32_e32 v138, 0, v138, vcc
	v_bfe_u32 v140, v140, 7, 9
	v_pk_fma_f32 v[138:139], v[138:139], v[154:155], v[152:153]
	v_and_b32_e32 v131, 0xff, v131
	v_and_b32_e32 v140, 0xff, v140
	v_pk_fma_f32 v[44:45], v[138:139], s[82:83], v[44:45] op_sel_hi:[1,0,1]
	s_waitcnt vmcnt(0)
	v_cvt_f32_i32_sdwa v139, sext(v144) dst_sel:DWORD dst_unused:UNUSED_PAD src0_sel:BYTE_1
	v_cvt_f32_i32_sdwa v138, sext(v144) dst_sel:DWORD dst_unused:UNUSED_PAD src0_sel:BYTE_0
	v_lshl_add_u32 v147, v131, 23, v233
	v_lshl_add_u32 v146, v140, 23, v233
	v_pk_mul_f32 v[146:147], v[146:147], s[34:35] op_sel_hi:[1,0]
	v_cmp_lt_u32_e32 vcc, 15, v131
	v_lshrrev_b32_e32 v131, 23, v142
	v_and_b32_e32 v131, 0xff, v131
	v_cndmask_b32_e32 v147, 0, v147, vcc
	v_cmp_lt_u32_e32 vcc, 15, v140
	v_bfe_u32 v140, v142, 7, 9
	v_and_b32_e32 v140, 0xff, v140
	v_cndmask_b32_e32 v146, 0, v146, vcc
	v_pk_fma_f32 v[46:47], v[148:149], s[82:83], v[46:47] op_sel_hi:[1,0,1]
	v_pk_fma_f32 v[136:137], v[146:147], v[138:139], v[136:137]
	v_cvt_f32_i32_sdwa v147, sext(v145) dst_sel:DWORD dst_unused:UNUSED_PAD src0_sel:BYTE_1
	v_cvt_f32_i32_sdwa v146, sext(v145) dst_sel:DWORD dst_unused:UNUSED_PAD src0_sel:BYTE_0
	v_lshl_add_u32 v149, v131, 23, v233
	v_lshl_add_u32 v148, v140, 23, v233
	v_pk_mul_f32 v[148:149], v[148:149], s[34:35] op_sel_hi:[1,0]
	v_cmp_lt_u32_e32 vcc, 15, v131
	v_lshrrev_b32_e32 v131, 23, v141
	v_lshlrev_b32_e32 v138, 16, v142
	v_cndmask_b32_e32 v149, 0, v149, vcc
	v_cmp_lt_u32_e32 vcc, 15, v140
	v_bfe_u32 v140, v141, 7, 9
	v_and_b32_e32 v139, 0xffff0000, v142
	v_cndmask_b32_e32 v148, 0, v148, vcc
	v_and_b32_e32 v131, 0xff, v131
	v_and_b32_e32 v142, 0xff, v140
	v_pk_fma_f32 v[138:139], v[148:149], v[146:147], v[138:139]
	v_lshlrev_b32_e32 v146, 16, v141
	v_and_b32_e32 v147, 0xffff0000, v141
	v_cvt_f32_i32_sdwa v149, sext(v144) dst_sel:DWORD dst_unused:UNUSED_PAD src0_sel:BYTE_3
	v_cvt_f32_i32_sdwa v148, sext(v144) dst_sel:DWORD dst_unused:UNUSED_PAD src0_sel:BYTE_2
	v_lshl_add_u32 v141, v131, 23, v233
	v_lshl_add_u32 v140, v142, 23, v233
	v_pk_mul_f32 v[140:141], v[140:141], s[34:35] op_sel_hi:[1,0]
	v_cmp_lt_u32_e32 vcc, 15, v131
	v_lshrrev_b32_e32 v131, 23, v143
	v_and_b32_e32 v131, 0xff, v131
	v_cndmask_b32_e32 v141, 0, v141, vcc
	v_cmp_lt_u32_e32 vcc, 15, v142
	v_bfe_u32 v142, v143, 7, 9
	v_and_b32_e32 v144, 0xff, v142
	v_cndmask_b32_e32 v140, 0, v140, vcc
	v_pk_fma_f32 v[140:141], v[140:141], v[148:149], v[146:147]
	v_lshlrev_b32_e32 v146, 16, v143
	v_and_b32_e32 v147, 0xffff0000, v143
	v_cvt_f32_i32_sdwa v149, sext(v145) dst_sel:DWORD dst_unused:UNUSED_PAD src0_sel:BYTE_3
	v_cvt_f32_i32_sdwa v148, sext(v145) dst_sel:DWORD dst_unused:UNUSED_PAD src0_sel:BYTE_2
	v_lshl_add_u32 v143, v131, 23, v233
	v_lshl_add_u32 v142, v144, 23, v233
	v_pk_mul_f32 v[142:143], v[142:143], s[34:35] op_sel_hi:[1,0]
	v_cmp_lt_u32_e32 vcc, 15, v131
	v_pk_fma_f32 v[40:41], v[140:141], s[82:83], v[40:41] op_sel_hi:[1,0,1]
	v_add_u32_e32 v140, 48, v130
	v_cndmask_b32_e32 v143, 0, v143, vcc
	v_cmp_lt_u32_e32 vcc, 15, v144
	v_ashrrev_i32_e32 v141, 31, v140
	v_pk_fma_f32 v[38:39], v[136:137], s[82:83], v[38:39] op_sel_hi:[1,0,1]
	v_cndmask_b32_e32 v142, 0, v142, vcc
	v_lshlrev_b64 v[136:137], 13, v[140:141]
	v_pk_fma_f32 v[142:143], v[142:143], v[148:149], v[146:147]
	v_lshl_add_u64 v[136:137], s[10:11], 0, v[136:137]
	v_pk_fma_f32 v[42:43], v[150:151], s[82:83], v[42:43] op_sel_hi:[1,0,1]
	v_pk_fma_f32 v[32:33], v[142:143], s[82:83], v[32:33] op_sel_hi:[1,0,1]
	v_pk_fma_f32 v[30:31], v[138:139], s[82:83], v[30:31] op_sel_hi:[1,0,1]
	v_lshl_add_u64 v[182:183], v[136:137], 0, v[132:133]
	global_load_dwordx4 v[136:139], v[182:183], off
	v_lshlrev_b64 v[194:195], 12, v[140:141]
	v_lshl_add_u64 v[140:141], s[0:1], 0, v[194:195]
	v_lshl_add_u64 v[144:145], v[140:141], 0, v[174:175]
	global_load_dwordx2 v[146:147], v[144:145], off
	global_load_dwordx4 v[140:143], v[182:183], off offset:256
	s_nop 0
	global_load_dwordx2 v[144:145], v[144:145], off offset:128
	s_waitcnt vmcnt(3)
	v_lshlrev_b32_e32 v148, 16, v136
	v_and_b32_e32 v149, 0xffff0000, v136
	v_lshrrev_b32_e32 v131, 23, v136
	v_bfe_u32 v136, v136, 7, 9
	v_and_b32_e32 v131, 0xff, v131
	v_and_b32_e32 v136, 0xff, v136
	s_waitcnt vmcnt(2)
	v_cvt_f32_i32_sdwa v151, sext(v146) dst_sel:DWORD dst_unused:UNUSED_PAD src0_sel:BYTE_1
	v_cvt_f32_i32_sdwa v150, sext(v146) dst_sel:DWORD dst_unused:UNUSED_PAD src0_sel:BYTE_0
	v_lshl_add_u32 v153, v131, 23, v233
	v_lshl_add_u32 v152, v136, 23, v233
	v_pk_mul_f32 v[152:153], v[152:153], s[34:35] op_sel_hi:[1,0]
	v_cmp_lt_u32_e32 vcc, 15, v131
	v_lshrrev_b32_e32 v131, 23, v138
	v_and_b32_e32 v131, 0xff, v131
	v_cndmask_b32_e32 v153, 0, v153, vcc
	v_cmp_lt_u32_e32 vcc, 15, v136
	v_bfe_u32 v136, v138, 7, 9
	v_and_b32_e32 v136, 0xff, v136
	v_cndmask_b32_e32 v152, 0, v152, vcc
	v_pk_fma_f32 v[148:149], v[152:153], v[150:151], v[148:149]
	v_cvt_f32_i32_sdwa v153, sext(v147) dst_sel:DWORD dst_unused:UNUSED_PAD src0_sel:BYTE_1
	v_cvt_f32_i32_sdwa v152, sext(v147) dst_sel:DWORD dst_unused:UNUSED_PAD src0_sel:BYTE_0
	v_lshl_add_u32 v155, v131, 23, v233
	v_lshl_add_u32 v154, v136, 23, v233
	v_pk_mul_f32 v[154:155], v[154:155], s[34:35] op_sel_hi:[1,0]
	v_cmp_lt_u32_e32 vcc, 15, v131
	v_lshrrev_b32_e32 v131, 23, v137
	v_lshlrev_b32_e32 v150, 16, v138
	v_cndmask_b32_e32 v155, 0, v155, vcc
	v_cmp_lt_u32_e32 vcc, 15, v136
	v_bfe_u32 v136, v137, 7, 9
	v_and_b32_e32 v151, 0xffff0000, v138
	v_cndmask_b32_e32 v154, 0, v154, vcc
	v_and_b32_e32 v131, 0xff, v131
	v_and_b32_e32 v138, 0xff, v136
	v_pk_fma_f32 v[150:151], v[154:155], v[152:153], v[150:151]
	v_lshlrev_b32_e32 v152, 16, v137
	v_and_b32_e32 v153, 0xffff0000, v137
	v_cvt_f32_i32_sdwa v155, sext(v146) dst_sel:DWORD dst_unused:UNUSED_PAD src0_sel:BYTE_3
	v_cvt_f32_i32_sdwa v154, sext(v146) dst_sel:DWORD dst_unused:UNUSED_PAD src0_sel:BYTE_2
	v_lshl_add_u32 v137, v131, 23, v233
	v_lshl_add_u32 v136, v138, 23, v233
	v_pk_mul_f32 v[136:137], v[136:137], s[34:35] op_sel_hi:[1,0]
	v_cmp_lt_u32_e32 vcc, 15, v131
	v_lshrrev_b32_e32 v131, 23, v139
	v_and_b32_e32 v131, 0xff, v131
	v_cndmask_b32_e32 v137, 0, v137, vcc
	v_cmp_lt_u32_e32 vcc, 15, v138
	v_bfe_u32 v138, v139, 7, 9
	v_and_b32_e32 v146, 0xff, v138
	v_cndmask_b32_e32 v136, 0, v136, vcc
	v_pk_fma_f32 v[136:137], v[136:137], v[154:155], v[152:153]
	v_lshlrev_b32_e32 v152, 16, v139
	v_and_b32_e32 v153, 0xffff0000, v139
	v_cvt_f32_i32_sdwa v155, sext(v147) dst_sel:DWORD dst_unused:UNUSED_PAD src0_sel:BYTE_3
	v_cvt_f32_i32_sdwa v154, sext(v147) dst_sel:DWORD dst_unused:UNUSED_PAD src0_sel:BYTE_2
	v_lshl_add_u32 v139, v131, 23, v233
	v_lshl_add_u32 v138, v146, 23, v233
	v_pk_mul_f32 v[138:139], v[138:139], s[34:35] op_sel_hi:[1,0]
	v_cmp_lt_u32_e32 vcc, 15, v131
	v_pk_fma_f32 v[64:65], v[136:137], s[82:83], v[64:65] op_sel_hi:[1,0,1]
	s_waitcnt vmcnt(1)
	v_lshlrev_b32_e32 v136, 16, v140
	v_cndmask_b32_e32 v139, 0, v139, vcc
	v_cmp_lt_u32_e32 vcc, 15, v146
	v_and_b32_e32 v137, 0xffff0000, v140
	v_lshrrev_b32_e32 v131, 23, v140
	v_cndmask_b32_e32 v138, 0, v138, vcc
	v_bfe_u32 v140, v140, 7, 9
	v_pk_fma_f32 v[138:139], v[138:139], v[154:155], v[152:153]
	v_and_b32_e32 v131, 0xff, v131
	v_and_b32_e32 v140, 0xff, v140
	v_pk_fma_f32 v[60:61], v[138:139], s[82:83], v[60:61] op_sel_hi:[1,0,1]
	s_waitcnt vmcnt(0)
	v_cvt_f32_i32_sdwa v139, sext(v144) dst_sel:DWORD dst_unused:UNUSED_PAD src0_sel:BYTE_1
	v_cvt_f32_i32_sdwa v138, sext(v144) dst_sel:DWORD dst_unused:UNUSED_PAD src0_sel:BYTE_0
	v_lshl_add_u32 v147, v131, 23, v233
	v_lshl_add_u32 v146, v140, 23, v233
	v_pk_mul_f32 v[146:147], v[146:147], s[34:35] op_sel_hi:[1,0]
	v_cmp_lt_u32_e32 vcc, 15, v131
	v_lshrrev_b32_e32 v131, 23, v142
	v_and_b32_e32 v131, 0xff, v131
	v_cndmask_b32_e32 v147, 0, v147, vcc
	v_cmp_lt_u32_e32 vcc, 15, v140
	v_bfe_u32 v140, v142, 7, 9
	v_and_b32_e32 v140, 0xff, v140
	v_cndmask_b32_e32 v146, 0, v146, vcc
	v_pk_fma_f32 v[62:63], v[148:149], s[82:83], v[62:63] op_sel_hi:[1,0,1]
	v_pk_fma_f32 v[136:137], v[146:147], v[138:139], v[136:137]
	v_cvt_f32_i32_sdwa v147, sext(v145) dst_sel:DWORD dst_unused:UNUSED_PAD src0_sel:BYTE_1
	v_cvt_f32_i32_sdwa v146, sext(v145) dst_sel:DWORD dst_unused:UNUSED_PAD src0_sel:BYTE_0
	v_lshl_add_u32 v149, v131, 23, v233
	v_lshl_add_u32 v148, v140, 23, v233
	v_pk_mul_f32 v[148:149], v[148:149], s[34:35] op_sel_hi:[1,0]
	v_cmp_lt_u32_e32 vcc, 15, v131
	v_lshrrev_b32_e32 v131, 23, v141
	v_lshlrev_b32_e32 v138, 16, v142
	v_cndmask_b32_e32 v149, 0, v149, vcc
	v_cmp_lt_u32_e32 vcc, 15, v140
	v_bfe_u32 v140, v141, 7, 9
	v_and_b32_e32 v139, 0xffff0000, v142
	v_cndmask_b32_e32 v148, 0, v148, vcc
	v_and_b32_e32 v131, 0xff, v131
	v_and_b32_e32 v142, 0xff, v140
	v_pk_fma_f32 v[138:139], v[148:149], v[146:147], v[138:139]
	v_lshlrev_b32_e32 v146, 16, v141
	v_and_b32_e32 v147, 0xffff0000, v141
	v_cvt_f32_i32_sdwa v149, sext(v144) dst_sel:DWORD dst_unused:UNUSED_PAD src0_sel:BYTE_3
	v_cvt_f32_i32_sdwa v148, sext(v144) dst_sel:DWORD dst_unused:UNUSED_PAD src0_sel:BYTE_2
	v_lshl_add_u32 v141, v131, 23, v233
	v_lshl_add_u32 v140, v142, 23, v233
	v_pk_mul_f32 v[140:141], v[140:141], s[34:35] op_sel_hi:[1,0]
	v_cmp_lt_u32_e32 vcc, 15, v131
	v_lshrrev_b32_e32 v131, 23, v143
	v_and_b32_e32 v131, 0xff, v131
	v_cndmask_b32_e32 v141, 0, v141, vcc
	v_cmp_lt_u32_e32 vcc, 15, v142
	v_bfe_u32 v142, v143, 7, 9
	v_and_b32_e32 v144, 0xff, v142
	v_cndmask_b32_e32 v140, 0, v140, vcc
	v_pk_fma_f32 v[140:141], v[140:141], v[148:149], v[146:147]
	v_lshlrev_b32_e32 v146, 16, v143
	v_and_b32_e32 v147, 0xffff0000, v143
	v_cvt_f32_i32_sdwa v149, sext(v145) dst_sel:DWORD dst_unused:UNUSED_PAD src0_sel:BYTE_3
	v_cvt_f32_i32_sdwa v148, sext(v145) dst_sel:DWORD dst_unused:UNUSED_PAD src0_sel:BYTE_2
	v_lshl_add_u32 v143, v131, 23, v233
	v_lshl_add_u32 v142, v144, 23, v233
	v_pk_mul_f32 v[142:143], v[142:143], s[34:35] op_sel_hi:[1,0]
	v_cmp_lt_u32_e32 vcc, 15, v131
	v_pk_fma_f32 v[56:57], v[140:141], s[82:83], v[56:57] op_sel_hi:[1,0,1]
	v_add_u32_e32 v140, 0x80, v130
	v_cndmask_b32_e32 v143, 0, v143, vcc
	v_cmp_lt_u32_e32 vcc, 15, v144
	v_ashrrev_i32_e32 v141, 31, v140
	v_pk_fma_f32 v[54:55], v[136:137], s[82:83], v[54:55] op_sel_hi:[1,0,1]
	v_cndmask_b32_e32 v142, 0, v142, vcc
	v_pk_fma_f32 v[142:143], v[142:143], v[148:149], v[146:147]
	v_lshlrev_b64 v[136:137], 13, v[140:141]
	v_pk_fma_f32 v[58:59], v[150:151], s[82:83], v[58:59] op_sel_hi:[1,0,1]
	v_pk_fma_f32 v[52:53], v[142:143], s[82:83], v[52:53] op_sel_hi:[1,0,1]
	v_pk_fma_f32 v[50:51], v[138:139], s[82:83], v[50:51] op_sel_hi:[1,0,1]
	v_lshl_add_u64 v[136:137], s[10:11], 0, v[136:137]
	v_lshl_add_u64 v[184:185], v[136:137], 0, v[132:133]
	global_load_dwordx4 v[136:139], v[184:185], off
	v_lshlrev_b64 v[204:205], 12, v[140:141]
	v_lshl_add_u64 v[140:141], s[0:1], 0, v[204:205]
	v_lshl_add_u64 v[144:145], v[140:141], 0, v[174:175]
	global_load_dwordx2 v[146:147], v[144:145], off
	global_load_dwordx4 v[140:143], v[184:185], off offset:256
	s_nop 0
	global_load_dwordx2 v[144:145], v[144:145], off offset:128
	s_waitcnt vmcnt(3)
	v_lshlrev_b32_e32 v148, 16, v136
	v_and_b32_e32 v149, 0xffff0000, v136
	v_lshrrev_b32_e32 v131, 23, v136
	v_bfe_u32 v136, v136, 7, 9
	v_and_b32_e32 v131, 0xff, v131
	v_and_b32_e32 v136, 0xff, v136
	s_waitcnt vmcnt(2)
	v_cvt_f32_i32_sdwa v151, sext(v146) dst_sel:DWORD dst_unused:UNUSED_PAD src0_sel:BYTE_1
	v_cvt_f32_i32_sdwa v150, sext(v146) dst_sel:DWORD dst_unused:UNUSED_PAD src0_sel:BYTE_0
	v_lshl_add_u32 v153, v131, 23, v233
	v_lshl_add_u32 v152, v136, 23, v233
	v_pk_mul_f32 v[152:153], v[152:153], s[34:35] op_sel_hi:[1,0]
	v_cmp_lt_u32_e32 vcc, 15, v131
	v_lshrrev_b32_e32 v131, 23, v138
	v_and_b32_e32 v131, 0xff, v131
	v_cndmask_b32_e32 v153, 0, v153, vcc
	v_cmp_lt_u32_e32 vcc, 15, v136
	v_bfe_u32 v136, v138, 7, 9
	v_and_b32_e32 v136, 0xff, v136
	v_cndmask_b32_e32 v152, 0, v152, vcc
	v_pk_fma_f32 v[148:149], v[152:153], v[150:151], v[148:149]
	v_cvt_f32_i32_sdwa v153, sext(v147) dst_sel:DWORD dst_unused:UNUSED_PAD src0_sel:BYTE_1
	v_cvt_f32_i32_sdwa v152, sext(v147) dst_sel:DWORD dst_unused:UNUSED_PAD src0_sel:BYTE_0
	v_lshl_add_u32 v155, v131, 23, v233
	v_lshl_add_u32 v154, v136, 23, v233
	v_pk_mul_f32 v[154:155], v[154:155], s[34:35] op_sel_hi:[1,0]
	v_cmp_lt_u32_e32 vcc, 15, v131
	v_lshrrev_b32_e32 v131, 23, v137
	v_lshlrev_b32_e32 v150, 16, v138
	v_cndmask_b32_e32 v155, 0, v155, vcc
	v_cmp_lt_u32_e32 vcc, 15, v136
	v_bfe_u32 v136, v137, 7, 9
	v_and_b32_e32 v151, 0xffff0000, v138
	v_cndmask_b32_e32 v154, 0, v154, vcc
	v_and_b32_e32 v131, 0xff, v131
	v_and_b32_e32 v138, 0xff, v136
	v_pk_fma_f32 v[150:151], v[154:155], v[152:153], v[150:151]
	v_lshlrev_b32_e32 v152, 16, v137
	v_and_b32_e32 v153, 0xffff0000, v137
	v_cvt_f32_i32_sdwa v155, sext(v146) dst_sel:DWORD dst_unused:UNUSED_PAD src0_sel:BYTE_3
	v_cvt_f32_i32_sdwa v154, sext(v146) dst_sel:DWORD dst_unused:UNUSED_PAD src0_sel:BYTE_2
	v_lshl_add_u32 v137, v131, 23, v233
	v_lshl_add_u32 v136, v138, 23, v233
	v_pk_mul_f32 v[136:137], v[136:137], s[34:35] op_sel_hi:[1,0]
	v_cmp_lt_u32_e32 vcc, 15, v131
	v_lshrrev_b32_e32 v131, 23, v139
	v_and_b32_e32 v131, 0xff, v131
	v_cndmask_b32_e32 v137, 0, v137, vcc
	v_cmp_lt_u32_e32 vcc, 15, v138
	v_bfe_u32 v138, v139, 7, 9
	v_and_b32_e32 v146, 0xff, v138
	v_cndmask_b32_e32 v136, 0, v136, vcc
	v_pk_fma_f32 v[136:137], v[136:137], v[154:155], v[152:153]
	v_lshlrev_b32_e32 v152, 16, v139
	v_and_b32_e32 v153, 0xffff0000, v139
	v_cvt_f32_i32_sdwa v155, sext(v147) dst_sel:DWORD dst_unused:UNUSED_PAD src0_sel:BYTE_3
	v_cvt_f32_i32_sdwa v154, sext(v147) dst_sel:DWORD dst_unused:UNUSED_PAD src0_sel:BYTE_2
	v_lshl_add_u32 v139, v131, 23, v233
	v_lshl_add_u32 v138, v146, 23, v233
	v_pk_mul_f32 v[138:139], v[138:139], s[34:35] op_sel_hi:[1,0]
	v_cmp_lt_u32_e32 vcc, 15, v131
	v_pk_fma_f32 v[80:81], v[136:137], s[82:83], v[80:81] op_sel_hi:[1,0,1]
	s_waitcnt vmcnt(1)
	v_lshlrev_b32_e32 v136, 16, v140
	v_cndmask_b32_e32 v139, 0, v139, vcc
	v_cmp_lt_u32_e32 vcc, 15, v146
	v_and_b32_e32 v137, 0xffff0000, v140
	v_lshrrev_b32_e32 v131, 23, v140
	v_cndmask_b32_e32 v138, 0, v138, vcc
	v_bfe_u32 v140, v140, 7, 9
	v_pk_fma_f32 v[138:139], v[138:139], v[154:155], v[152:153]
	v_and_b32_e32 v131, 0xff, v131
	v_and_b32_e32 v140, 0xff, v140
	v_pk_fma_f32 v[76:77], v[138:139], s[82:83], v[76:77] op_sel_hi:[1,0,1]
	s_waitcnt vmcnt(0)
	v_cvt_f32_i32_sdwa v139, sext(v144) dst_sel:DWORD dst_unused:UNUSED_PAD src0_sel:BYTE_1
	v_cvt_f32_i32_sdwa v138, sext(v144) dst_sel:DWORD dst_unused:UNUSED_PAD src0_sel:BYTE_0
	v_lshl_add_u32 v147, v131, 23, v233
	v_lshl_add_u32 v146, v140, 23, v233
	v_pk_mul_f32 v[146:147], v[146:147], s[34:35] op_sel_hi:[1,0]
	v_cmp_lt_u32_e32 vcc, 15, v131
	v_lshrrev_b32_e32 v131, 23, v142
	v_and_b32_e32 v131, 0xff, v131
	v_cndmask_b32_e32 v147, 0, v147, vcc
	v_cmp_lt_u32_e32 vcc, 15, v140
	v_bfe_u32 v140, v142, 7, 9
	v_and_b32_e32 v140, 0xff, v140
	v_cndmask_b32_e32 v146, 0, v146, vcc
	v_pk_fma_f32 v[78:79], v[148:149], s[82:83], v[78:79] op_sel_hi:[1,0,1]
	v_pk_fma_f32 v[136:137], v[146:147], v[138:139], v[136:137]
	v_cvt_f32_i32_sdwa v147, sext(v145) dst_sel:DWORD dst_unused:UNUSED_PAD src0_sel:BYTE_1
	v_cvt_f32_i32_sdwa v146, sext(v145) dst_sel:DWORD dst_unused:UNUSED_PAD src0_sel:BYTE_0
	v_lshl_add_u32 v149, v131, 23, v233
	v_lshl_add_u32 v148, v140, 23, v233
	v_pk_mul_f32 v[148:149], v[148:149], s[34:35] op_sel_hi:[1,0]
	v_cmp_lt_u32_e32 vcc, 15, v131
	v_lshrrev_b32_e32 v131, 23, v141
	v_lshlrev_b32_e32 v138, 16, v142
	v_cndmask_b32_e32 v149, 0, v149, vcc
	v_cmp_lt_u32_e32 vcc, 15, v140
	v_bfe_u32 v140, v141, 7, 9
	v_and_b32_e32 v139, 0xffff0000, v142
	v_cndmask_b32_e32 v148, 0, v148, vcc
	v_and_b32_e32 v131, 0xff, v131
	v_and_b32_e32 v142, 0xff, v140
	v_pk_fma_f32 v[138:139], v[148:149], v[146:147], v[138:139]
	v_lshlrev_b32_e32 v146, 16, v141
	v_and_b32_e32 v147, 0xffff0000, v141
	v_cvt_f32_i32_sdwa v149, sext(v144) dst_sel:DWORD dst_unused:UNUSED_PAD src0_sel:BYTE_3
	v_cvt_f32_i32_sdwa v148, sext(v144) dst_sel:DWORD dst_unused:UNUSED_PAD src0_sel:BYTE_2
	v_lshl_add_u32 v141, v131, 23, v233
	v_lshl_add_u32 v140, v142, 23, v233
	v_pk_mul_f32 v[140:141], v[140:141], s[34:35] op_sel_hi:[1,0]
	v_cmp_lt_u32_e32 vcc, 15, v131
	v_lshrrev_b32_e32 v131, 23, v143
	v_and_b32_e32 v131, 0xff, v131
	v_cndmask_b32_e32 v141, 0, v141, vcc
	v_cmp_lt_u32_e32 vcc, 15, v142
	v_bfe_u32 v142, v143, 7, 9
	v_and_b32_e32 v144, 0xff, v142
	v_cndmask_b32_e32 v140, 0, v140, vcc
	v_pk_fma_f32 v[140:141], v[140:141], v[148:149], v[146:147]
	v_lshlrev_b32_e32 v146, 16, v143
	v_and_b32_e32 v147, 0xffff0000, v143
	v_cvt_f32_i32_sdwa v149, sext(v145) dst_sel:DWORD dst_unused:UNUSED_PAD src0_sel:BYTE_3
	v_cvt_f32_i32_sdwa v148, sext(v145) dst_sel:DWORD dst_unused:UNUSED_PAD src0_sel:BYTE_2
	v_lshl_add_u32 v143, v131, 23, v233
	v_lshl_add_u32 v142, v144, 23, v233
	v_pk_mul_f32 v[142:143], v[142:143], s[34:35] op_sel_hi:[1,0]
	v_cmp_lt_u32_e32 vcc, 15, v131
	v_pk_fma_f32 v[72:73], v[140:141], s[82:83], v[72:73] op_sel_hi:[1,0,1]
	v_add_u32_e32 v140, 0x90, v130
	v_cndmask_b32_e32 v143, 0, v143, vcc
	v_cmp_lt_u32_e32 vcc, 15, v144
	v_ashrrev_i32_e32 v141, 31, v140
	v_pk_fma_f32 v[70:71], v[136:137], s[82:83], v[70:71] op_sel_hi:[1,0,1]
	v_cndmask_b32_e32 v142, 0, v142, vcc
	v_lshlrev_b64 v[136:137], 13, v[140:141]
	v_pk_fma_f32 v[142:143], v[142:143], v[148:149], v[146:147]
	v_lshl_add_u64 v[136:137], s[10:11], 0, v[136:137]
	v_pk_fma_f32 v[74:75], v[150:151], s[82:83], v[74:75] op_sel_hi:[1,0,1]
	v_pk_fma_f32 v[68:69], v[142:143], s[82:83], v[68:69] op_sel_hi:[1,0,1]
	v_pk_fma_f32 v[66:67], v[138:139], s[82:83], v[66:67] op_sel_hi:[1,0,1]
	v_lshl_add_u64 v[192:193], v[136:137], 0, v[132:133]
	global_load_dwordx4 v[136:139], v[192:193], off
	v_lshlrev_b64 v[208:209], 12, v[140:141]
	v_lshl_add_u64 v[140:141], s[0:1], 0, v[208:209]
	v_lshl_add_u64 v[144:145], v[140:141], 0, v[174:175]
	global_load_dwordx2 v[146:147], v[144:145], off
	global_load_dwordx4 v[140:143], v[192:193], off offset:256
	s_nop 0
	global_load_dwordx2 v[144:145], v[144:145], off offset:128
	s_waitcnt vmcnt(3)
	v_lshlrev_b32_e32 v148, 16, v136
	v_and_b32_e32 v149, 0xffff0000, v136
	v_lshrrev_b32_e32 v131, 23, v136
	v_bfe_u32 v136, v136, 7, 9
	v_and_b32_e32 v131, 0xff, v131
	v_and_b32_e32 v136, 0xff, v136
	s_waitcnt vmcnt(2)
	v_cvt_f32_i32_sdwa v151, sext(v146) dst_sel:DWORD dst_unused:UNUSED_PAD src0_sel:BYTE_1
	v_cvt_f32_i32_sdwa v150, sext(v146) dst_sel:DWORD dst_unused:UNUSED_PAD src0_sel:BYTE_0
	v_lshl_add_u32 v153, v131, 23, v233
	v_lshl_add_u32 v152, v136, 23, v233
	v_pk_mul_f32 v[152:153], v[152:153], s[34:35] op_sel_hi:[1,0]
	v_cmp_lt_u32_e32 vcc, 15, v131
	v_lshrrev_b32_e32 v131, 23, v138
	v_and_b32_e32 v131, 0xff, v131
	v_cndmask_b32_e32 v153, 0, v153, vcc
	v_cmp_lt_u32_e32 vcc, 15, v136
	v_bfe_u32 v136, v138, 7, 9
	v_and_b32_e32 v136, 0xff, v136
	v_cndmask_b32_e32 v152, 0, v152, vcc
	v_pk_fma_f32 v[148:149], v[152:153], v[150:151], v[148:149]
	v_cvt_f32_i32_sdwa v153, sext(v147) dst_sel:DWORD dst_unused:UNUSED_PAD src0_sel:BYTE_1
	v_cvt_f32_i32_sdwa v152, sext(v147) dst_sel:DWORD dst_unused:UNUSED_PAD src0_sel:BYTE_0
	v_lshl_add_u32 v155, v131, 23, v233
	v_lshl_add_u32 v154, v136, 23, v233
	v_pk_mul_f32 v[154:155], v[154:155], s[34:35] op_sel_hi:[1,0]
	v_cmp_lt_u32_e32 vcc, 15, v131
	v_lshrrev_b32_e32 v131, 23, v137
	v_lshlrev_b32_e32 v150, 16, v138
	v_cndmask_b32_e32 v155, 0, v155, vcc
	v_cmp_lt_u32_e32 vcc, 15, v136
	v_bfe_u32 v136, v137, 7, 9
	v_and_b32_e32 v151, 0xffff0000, v138
	v_cndmask_b32_e32 v154, 0, v154, vcc
	v_and_b32_e32 v131, 0xff, v131
	v_and_b32_e32 v138, 0xff, v136
	v_pk_fma_f32 v[150:151], v[154:155], v[152:153], v[150:151]
	v_lshlrev_b32_e32 v152, 16, v137
	v_and_b32_e32 v153, 0xffff0000, v137
	v_cvt_f32_i32_sdwa v155, sext(v146) dst_sel:DWORD dst_unused:UNUSED_PAD src0_sel:BYTE_3
	v_cvt_f32_i32_sdwa v154, sext(v146) dst_sel:DWORD dst_unused:UNUSED_PAD src0_sel:BYTE_2
	v_lshl_add_u32 v137, v131, 23, v233
	v_lshl_add_u32 v136, v138, 23, v233
	v_pk_mul_f32 v[136:137], v[136:137], s[34:35] op_sel_hi:[1,0]
	v_cmp_lt_u32_e32 vcc, 15, v131
	v_lshrrev_b32_e32 v131, 23, v139
	v_and_b32_e32 v131, 0xff, v131
	v_cndmask_b32_e32 v137, 0, v137, vcc
	v_cmp_lt_u32_e32 vcc, 15, v138
	v_bfe_u32 v138, v139, 7, 9
	v_and_b32_e32 v146, 0xff, v138
	v_cndmask_b32_e32 v136, 0, v136, vcc
	v_pk_fma_f32 v[136:137], v[136:137], v[154:155], v[152:153]
	v_lshlrev_b32_e32 v152, 16, v139
	v_and_b32_e32 v153, 0xffff0000, v139
	v_cvt_f32_i32_sdwa v155, sext(v147) dst_sel:DWORD dst_unused:UNUSED_PAD src0_sel:BYTE_3
	v_cvt_f32_i32_sdwa v154, sext(v147) dst_sel:DWORD dst_unused:UNUSED_PAD src0_sel:BYTE_2
	v_lshl_add_u32 v139, v131, 23, v233
	v_lshl_add_u32 v138, v146, 23, v233
	v_pk_mul_f32 v[138:139], v[138:139], s[34:35] op_sel_hi:[1,0]
	v_cmp_lt_u32_e32 vcc, 15, v131
	v_pk_fma_f32 v[96:97], v[136:137], s[82:83], v[96:97] op_sel_hi:[1,0,1]
	s_waitcnt vmcnt(1)
	v_lshlrev_b32_e32 v136, 16, v140
	v_cndmask_b32_e32 v139, 0, v139, vcc
	v_cmp_lt_u32_e32 vcc, 15, v146
	v_and_b32_e32 v137, 0xffff0000, v140
	v_lshrrev_b32_e32 v131, 23, v140
	v_cndmask_b32_e32 v138, 0, v138, vcc
	v_bfe_u32 v140, v140, 7, 9
	v_pk_fma_f32 v[138:139], v[138:139], v[154:155], v[152:153]
	v_and_b32_e32 v131, 0xff, v131
	v_and_b32_e32 v140, 0xff, v140
	v_pk_fma_f32 v[92:93], v[138:139], s[82:83], v[92:93] op_sel_hi:[1,0,1]
	s_waitcnt vmcnt(0)
	v_cvt_f32_i32_sdwa v139, sext(v144) dst_sel:DWORD dst_unused:UNUSED_PAD src0_sel:BYTE_1
	v_cvt_f32_i32_sdwa v138, sext(v144) dst_sel:DWORD dst_unused:UNUSED_PAD src0_sel:BYTE_0
	v_lshl_add_u32 v147, v131, 23, v233
	v_lshl_add_u32 v146, v140, 23, v233
	v_pk_mul_f32 v[146:147], v[146:147], s[34:35] op_sel_hi:[1,0]
	v_cmp_lt_u32_e32 vcc, 15, v131
	v_lshrrev_b32_e32 v131, 23, v142
	v_and_b32_e32 v131, 0xff, v131
	v_cndmask_b32_e32 v147, 0, v147, vcc
	v_cmp_lt_u32_e32 vcc, 15, v140
	v_bfe_u32 v140, v142, 7, 9
	v_and_b32_e32 v140, 0xff, v140
	v_cndmask_b32_e32 v146, 0, v146, vcc
	v_pk_fma_f32 v[94:95], v[148:149], s[82:83], v[94:95] op_sel_hi:[1,0,1]
	v_pk_fma_f32 v[136:137], v[146:147], v[138:139], v[136:137]
	v_cvt_f32_i32_sdwa v147, sext(v145) dst_sel:DWORD dst_unused:UNUSED_PAD src0_sel:BYTE_1
	v_cvt_f32_i32_sdwa v146, sext(v145) dst_sel:DWORD dst_unused:UNUSED_PAD src0_sel:BYTE_0
	v_lshl_add_u32 v149, v131, 23, v233
	v_lshl_add_u32 v148, v140, 23, v233
	v_pk_mul_f32 v[148:149], v[148:149], s[34:35] op_sel_hi:[1,0]
	v_cmp_lt_u32_e32 vcc, 15, v131
	v_lshrrev_b32_e32 v131, 23, v141
	v_lshlrev_b32_e32 v138, 16, v142
	v_cndmask_b32_e32 v149, 0, v149, vcc
	v_cmp_lt_u32_e32 vcc, 15, v140
	v_bfe_u32 v140, v141, 7, 9
	v_and_b32_e32 v139, 0xffff0000, v142
	v_cndmask_b32_e32 v148, 0, v148, vcc
	v_and_b32_e32 v131, 0xff, v131
	v_and_b32_e32 v142, 0xff, v140
	v_pk_fma_f32 v[138:139], v[148:149], v[146:147], v[138:139]
	v_lshlrev_b32_e32 v146, 16, v141
	v_and_b32_e32 v147, 0xffff0000, v141
	v_cvt_f32_i32_sdwa v149, sext(v144) dst_sel:DWORD dst_unused:UNUSED_PAD src0_sel:BYTE_3
	v_cvt_f32_i32_sdwa v148, sext(v144) dst_sel:DWORD dst_unused:UNUSED_PAD src0_sel:BYTE_2
	v_lshl_add_u32 v141, v131, 23, v233
	v_lshl_add_u32 v140, v142, 23, v233
	v_pk_mul_f32 v[140:141], v[140:141], s[34:35] op_sel_hi:[1,0]
	v_cmp_lt_u32_e32 vcc, 15, v131
	v_lshrrev_b32_e32 v131, 23, v143
	v_and_b32_e32 v131, 0xff, v131
	v_cndmask_b32_e32 v141, 0, v141, vcc
	v_cmp_lt_u32_e32 vcc, 15, v142
	v_bfe_u32 v142, v143, 7, 9
	v_and_b32_e32 v144, 0xff, v142
	v_cndmask_b32_e32 v140, 0, v140, vcc
	v_pk_fma_f32 v[140:141], v[140:141], v[148:149], v[146:147]
	v_lshlrev_b32_e32 v146, 16, v143
	v_and_b32_e32 v147, 0xffff0000, v143
	v_cvt_f32_i32_sdwa v149, sext(v145) dst_sel:DWORD dst_unused:UNUSED_PAD src0_sel:BYTE_3
	v_cvt_f32_i32_sdwa v148, sext(v145) dst_sel:DWORD dst_unused:UNUSED_PAD src0_sel:BYTE_2
	v_lshl_add_u32 v143, v131, 23, v233
	v_lshl_add_u32 v142, v144, 23, v233
	v_pk_mul_f32 v[142:143], v[142:143], s[34:35] op_sel_hi:[1,0]
	v_cmp_lt_u32_e32 vcc, 15, v131
	v_pk_fma_f32 v[88:89], v[140:141], s[82:83], v[88:89] op_sel_hi:[1,0,1]
	v_add_u32_e32 v140, 0xa0, v130
	v_cndmask_b32_e32 v143, 0, v143, vcc
	v_cmp_lt_u32_e32 vcc, 15, v144
	v_ashrrev_i32_e32 v141, 31, v140
	v_pk_fma_f32 v[86:87], v[136:137], s[82:83], v[86:87] op_sel_hi:[1,0,1]
	v_cndmask_b32_e32 v142, 0, v142, vcc
	v_lshlrev_b64 v[136:137], 13, v[140:141]
	v_pk_fma_f32 v[142:143], v[142:143], v[148:149], v[146:147]
	v_lshl_add_u64 v[136:137], s[10:11], 0, v[136:137]
	v_pk_fma_f32 v[90:91], v[150:151], s[82:83], v[90:91] op_sel_hi:[1,0,1]
	v_pk_fma_f32 v[84:85], v[142:143], s[82:83], v[84:85] op_sel_hi:[1,0,1]
	v_pk_fma_f32 v[82:83], v[138:139], s[82:83], v[82:83] op_sel_hi:[1,0,1]
	v_lshl_add_u64 v[202:203], v[136:137], 0, v[132:133]
	global_load_dwordx4 v[136:139], v[202:203], off
	v_lshlrev_b64 v[210:211], 12, v[140:141]
	v_lshl_add_u64 v[140:141], s[0:1], 0, v[210:211]
	v_lshl_add_u64 v[144:145], v[140:141], 0, v[174:175]
	global_load_dwordx2 v[146:147], v[144:145], off
	global_load_dwordx4 v[140:143], v[202:203], off offset:256
	s_nop 0
	global_load_dwordx2 v[144:145], v[144:145], off offset:128
	s_waitcnt vmcnt(3)
	v_lshlrev_b32_e32 v148, 16, v136
	v_and_b32_e32 v149, 0xffff0000, v136
	v_lshrrev_b32_e32 v131, 23, v136
	v_bfe_u32 v136, v136, 7, 9
	v_and_b32_e32 v131, 0xff, v131
	v_and_b32_e32 v136, 0xff, v136
	s_waitcnt vmcnt(2)
	v_cvt_f32_i32_sdwa v151, sext(v146) dst_sel:DWORD dst_unused:UNUSED_PAD src0_sel:BYTE_1
	v_cvt_f32_i32_sdwa v150, sext(v146) dst_sel:DWORD dst_unused:UNUSED_PAD src0_sel:BYTE_0
	v_lshl_add_u32 v153, v131, 23, v233
	v_lshl_add_u32 v152, v136, 23, v233
	v_pk_mul_f32 v[152:153], v[152:153], s[34:35] op_sel_hi:[1,0]
	v_cmp_lt_u32_e32 vcc, 15, v131
	v_lshrrev_b32_e32 v131, 23, v138
	v_and_b32_e32 v131, 0xff, v131
	v_cndmask_b32_e32 v153, 0, v153, vcc
	v_cmp_lt_u32_e32 vcc, 15, v136
	v_bfe_u32 v136, v138, 7, 9
	v_and_b32_e32 v136, 0xff, v136
	v_cndmask_b32_e32 v152, 0, v152, vcc
	v_pk_fma_f32 v[148:149], v[152:153], v[150:151], v[148:149]
	v_cvt_f32_i32_sdwa v153, sext(v147) dst_sel:DWORD dst_unused:UNUSED_PAD src0_sel:BYTE_1
	v_cvt_f32_i32_sdwa v152, sext(v147) dst_sel:DWORD dst_unused:UNUSED_PAD src0_sel:BYTE_0
	v_lshl_add_u32 v155, v131, 23, v233
	v_lshl_add_u32 v154, v136, 23, v233
	v_pk_mul_f32 v[154:155], v[154:155], s[34:35] op_sel_hi:[1,0]
	v_cmp_lt_u32_e32 vcc, 15, v131
	v_lshrrev_b32_e32 v131, 23, v137
	v_lshlrev_b32_e32 v150, 16, v138
	v_cndmask_b32_e32 v155, 0, v155, vcc
	v_cmp_lt_u32_e32 vcc, 15, v136
	v_bfe_u32 v136, v137, 7, 9
	v_and_b32_e32 v151, 0xffff0000, v138
	v_cndmask_b32_e32 v154, 0, v154, vcc
	v_and_b32_e32 v131, 0xff, v131
	v_and_b32_e32 v138, 0xff, v136
	v_pk_fma_f32 v[150:151], v[154:155], v[152:153], v[150:151]
	v_lshlrev_b32_e32 v152, 16, v137
	v_and_b32_e32 v153, 0xffff0000, v137
	v_cvt_f32_i32_sdwa v155, sext(v146) dst_sel:DWORD dst_unused:UNUSED_PAD src0_sel:BYTE_3
	v_cvt_f32_i32_sdwa v154, sext(v146) dst_sel:DWORD dst_unused:UNUSED_PAD src0_sel:BYTE_2
	v_lshl_add_u32 v137, v131, 23, v233
	v_lshl_add_u32 v136, v138, 23, v233
	v_pk_mul_f32 v[136:137], v[136:137], s[34:35] op_sel_hi:[1,0]
	v_cmp_lt_u32_e32 vcc, 15, v131
	v_lshrrev_b32_e32 v131, 23, v139
	v_and_b32_e32 v131, 0xff, v131
	v_cndmask_b32_e32 v137, 0, v137, vcc
	v_cmp_lt_u32_e32 vcc, 15, v138
	v_bfe_u32 v138, v139, 7, 9
	v_and_b32_e32 v146, 0xff, v138
	v_cndmask_b32_e32 v136, 0, v136, vcc
	v_pk_fma_f32 v[136:137], v[136:137], v[154:155], v[152:153]
	v_lshlrev_b32_e32 v152, 16, v139
	v_and_b32_e32 v153, 0xffff0000, v139
	v_cvt_f32_i32_sdwa v155, sext(v147) dst_sel:DWORD dst_unused:UNUSED_PAD src0_sel:BYTE_3
	v_cvt_f32_i32_sdwa v154, sext(v147) dst_sel:DWORD dst_unused:UNUSED_PAD src0_sel:BYTE_2
	v_lshl_add_u32 v139, v131, 23, v233
	v_lshl_add_u32 v138, v146, 23, v233
	v_pk_mul_f32 v[138:139], v[138:139], s[34:35] op_sel_hi:[1,0]
	v_cmp_lt_u32_e32 vcc, 15, v131
	v_pk_fma_f32 v[112:113], v[136:137], s[82:83], v[112:113] op_sel_hi:[1,0,1]
	s_waitcnt vmcnt(1)
	v_lshlrev_b32_e32 v136, 16, v140
	v_cndmask_b32_e32 v139, 0, v139, vcc
	v_cmp_lt_u32_e32 vcc, 15, v146
	v_and_b32_e32 v137, 0xffff0000, v140
	v_lshrrev_b32_e32 v131, 23, v140
	v_cndmask_b32_e32 v138, 0, v138, vcc
	v_bfe_u32 v140, v140, 7, 9
	v_pk_fma_f32 v[138:139], v[138:139], v[154:155], v[152:153]
	v_and_b32_e32 v131, 0xff, v131
	v_and_b32_e32 v140, 0xff, v140
	v_pk_fma_f32 v[108:109], v[138:139], s[82:83], v[108:109] op_sel_hi:[1,0,1]
	s_waitcnt vmcnt(0)
	v_cvt_f32_i32_sdwa v139, sext(v144) dst_sel:DWORD dst_unused:UNUSED_PAD src0_sel:BYTE_1
	v_cvt_f32_i32_sdwa v138, sext(v144) dst_sel:DWORD dst_unused:UNUSED_PAD src0_sel:BYTE_0
	v_lshl_add_u32 v147, v131, 23, v233
	v_lshl_add_u32 v146, v140, 23, v233
	v_pk_mul_f32 v[146:147], v[146:147], s[34:35] op_sel_hi:[1,0]
	v_cmp_lt_u32_e32 vcc, 15, v131
	v_lshrrev_b32_e32 v131, 23, v142
	v_and_b32_e32 v131, 0xff, v131
	v_cndmask_b32_e32 v147, 0, v147, vcc
	v_cmp_lt_u32_e32 vcc, 15, v140
	v_bfe_u32 v140, v142, 7, 9
	v_and_b32_e32 v140, 0xff, v140
	v_cndmask_b32_e32 v146, 0, v146, vcc
	v_pk_fma_f32 v[110:111], v[148:149], s[82:83], v[110:111] op_sel_hi:[1,0,1]
	v_pk_fma_f32 v[136:137], v[146:147], v[138:139], v[136:137]
	v_cvt_f32_i32_sdwa v147, sext(v145) dst_sel:DWORD dst_unused:UNUSED_PAD src0_sel:BYTE_1
	v_cvt_f32_i32_sdwa v146, sext(v145) dst_sel:DWORD dst_unused:UNUSED_PAD src0_sel:BYTE_0
	v_lshl_add_u32 v149, v131, 23, v233
	v_lshl_add_u32 v148, v140, 23, v233
	v_pk_mul_f32 v[148:149], v[148:149], s[34:35] op_sel_hi:[1,0]
	v_cmp_lt_u32_e32 vcc, 15, v131
	v_lshrrev_b32_e32 v131, 23, v141
	v_lshlrev_b32_e32 v138, 16, v142
	v_cndmask_b32_e32 v149, 0, v149, vcc
	v_cmp_lt_u32_e32 vcc, 15, v140
	v_bfe_u32 v140, v141, 7, 9
	v_and_b32_e32 v139, 0xffff0000, v142
	v_cndmask_b32_e32 v148, 0, v148, vcc
	v_and_b32_e32 v131, 0xff, v131
	v_and_b32_e32 v142, 0xff, v140
	v_pk_fma_f32 v[138:139], v[148:149], v[146:147], v[138:139]
	v_lshlrev_b32_e32 v146, 16, v141
	v_and_b32_e32 v147, 0xffff0000, v141
	v_cvt_f32_i32_sdwa v149, sext(v144) dst_sel:DWORD dst_unused:UNUSED_PAD src0_sel:BYTE_3
	v_cvt_f32_i32_sdwa v148, sext(v144) dst_sel:DWORD dst_unused:UNUSED_PAD src0_sel:BYTE_2
	v_lshl_add_u32 v141, v131, 23, v233
	v_lshl_add_u32 v140, v142, 23, v233
	v_pk_mul_f32 v[140:141], v[140:141], s[34:35] op_sel_hi:[1,0]
	v_cmp_lt_u32_e32 vcc, 15, v131
	v_lshrrev_b32_e32 v131, 23, v143
	v_and_b32_e32 v131, 0xff, v131
	v_cndmask_b32_e32 v141, 0, v141, vcc
	v_cmp_lt_u32_e32 vcc, 15, v142
	v_bfe_u32 v142, v143, 7, 9
	v_and_b32_e32 v144, 0xff, v142
	v_cndmask_b32_e32 v140, 0, v140, vcc
	v_pk_fma_f32 v[140:141], v[140:141], v[148:149], v[146:147]
	v_lshlrev_b32_e32 v146, 16, v143
	v_and_b32_e32 v147, 0xffff0000, v143
	v_cvt_f32_i32_sdwa v149, sext(v145) dst_sel:DWORD dst_unused:UNUSED_PAD src0_sel:BYTE_3
	v_cvt_f32_i32_sdwa v148, sext(v145) dst_sel:DWORD dst_unused:UNUSED_PAD src0_sel:BYTE_2
	v_lshl_add_u32 v143, v131, 23, v233
	v_lshl_add_u32 v142, v144, 23, v233
	v_pk_mul_f32 v[142:143], v[142:143], s[34:35] op_sel_hi:[1,0]
	v_cmp_lt_u32_e32 vcc, 15, v131
	v_pk_fma_f32 v[102:103], v[136:137], s[82:83], v[102:103] op_sel_hi:[1,0,1]
	v_add_u32_e32 v136, 0xb0, v130
	v_cndmask_b32_e32 v143, 0, v143, vcc
	v_cmp_lt_u32_e32 vcc, 15, v144
	v_ashrrev_i32_e32 v137, 31, v136
	v_lshlrev_b64 v[130:131], 13, v[136:137]
	v_cndmask_b32_e32 v142, 0, v142, vcc
	v_pk_fma_f32 v[142:143], v[142:143], v[148:149], v[146:147]
	v_lshl_add_u64 v[130:131], s[10:11], 0, v[130:131]
	v_pk_fma_f32 v[106:107], v[150:151], s[82:83], v[106:107] op_sel_hi:[1,0,1]
	v_pk_fma_f32 v[104:105], v[140:141], s[82:83], v[104:105] op_sel_hi:[1,0,1]
	v_pk_fma_f32 v[100:101], v[142:143], s[82:83], v[100:101] op_sel_hi:[1,0,1]
	v_pk_fma_f32 v[98:99], v[138:139], s[82:83], v[98:99] op_sel_hi:[1,0,1]
	v_lshl_add_u64 v[206:207], v[130:131], 0, v[132:133]
	global_load_dwordx4 v[130:133], v[206:207], off
	v_lshlrev_b64 v[212:213], 12, v[136:137]
	v_lshl_add_u64 v[136:137], s[0:1], 0, v[212:213]
	v_lshl_add_u64 v[140:141], v[136:137], 0, v[174:175]
	global_load_dwordx2 v[142:143], v[140:141], off
	global_load_dwordx4 v[136:139], v[206:207], off offset:256
	s_nop 0
	global_load_dwordx2 v[140:141], v[140:141], off offset:128
	s_waitcnt vmcnt(3)
	v_lshlrev_b32_e32 v144, 16, v130
	v_and_b32_e32 v145, 0xffff0000, v130
	v_lshrrev_b32_e32 v148, 23, v130
	v_bfe_u32 v130, v130, 7, 9
	v_and_b32_e32 v150, 0xff, v148
	v_and_b32_e32 v130, 0xff, v130
	s_waitcnt vmcnt(2)
	v_cvt_f32_i32_sdwa v147, sext(v142) dst_sel:DWORD dst_unused:UNUSED_PAD src0_sel:BYTE_1
	v_cvt_f32_i32_sdwa v146, sext(v142) dst_sel:DWORD dst_unused:UNUSED_PAD src0_sel:BYTE_0
	v_lshl_add_u32 v149, v150, 23, v233
	v_lshl_add_u32 v148, v130, 23, v233
	v_pk_mul_f32 v[148:149], v[148:149], s[34:35] op_sel_hi:[1,0]
	v_cmp_lt_u32_e32 vcc, 15, v150
	s_nop 1
	v_cndmask_b32_e32 v149, 0, v149, vcc
	v_cmp_lt_u32_e32 vcc, 15, v130
	v_lshrrev_b32_e32 v130, 23, v132
	v_and_b32_e32 v130, 0xff, v130
	v_cndmask_b32_e32 v148, 0, v148, vcc
	v_pk_fma_f32 v[144:145], v[148:149], v[146:147], v[144:145]
	v_lshlrev_b32_e32 v146, 16, v132
	v_and_b32_e32 v147, 0xffff0000, v132
	v_bfe_u32 v132, v132, 7, 9
	v_and_b32_e32 v132, 0xff, v132
	v_cvt_f32_i32_sdwa v149, sext(v143) dst_sel:DWORD dst_unused:UNUSED_PAD src0_sel:BYTE_1
	v_cvt_f32_i32_sdwa v148, sext(v143) dst_sel:DWORD dst_unused:UNUSED_PAD src0_sel:BYTE_0
	v_lshl_add_u32 v151, v130, 23, v233
	v_lshl_add_u32 v150, v132, 23, v233
	v_pk_mul_f32 v[150:151], v[150:151], s[34:35] op_sel_hi:[1,0]
	v_cmp_lt_u32_e32 vcc, 15, v130
	v_lshrrev_b32_e32 v130, 23, v131
	v_pk_fma_f32 v[118:119], v[144:145], s[82:83], v[118:119] op_sel_hi:[1,0,1]
	v_cndmask_b32_e32 v151, 0, v151, vcc
	v_cmp_lt_u32_e32 vcc, 15, v132
	v_and_b32_e32 v132, 0xff, v130
	s_nop 0
	v_cndmask_b32_e32 v150, 0, v150, vcc
	v_pk_fma_f32 v[146:147], v[150:151], v[148:149], v[146:147]
	v_lshlrev_b32_e32 v148, 16, v131
	v_and_b32_e32 v149, 0xffff0000, v131
	v_bfe_u32 v131, v131, 7, 9
	v_cvt_f32_i32_sdwa v151, sext(v142) dst_sel:DWORD dst_unused:UNUSED_PAD src0_sel:BYTE_3
	v_cvt_f32_i32_sdwa v150, sext(v142) dst_sel:DWORD dst_unused:UNUSED_PAD src0_sel:BYTE_2
	v_and_b32_e32 v142, 0xff, v131
	v_lshl_add_u32 v131, v132, 23, v233
	v_lshl_add_u32 v130, v142, 23, v233
	v_pk_mul_f32 v[130:131], v[130:131], s[34:35] op_sel_hi:[1,0]
	v_cmp_lt_u32_e32 vcc, 15, v132
	v_lshrrev_b32_e32 v132, 23, v133
	v_pk_fma_f32 v[114:115], v[146:147], s[82:83], v[114:115] op_sel_hi:[1,0,1]
	v_cndmask_b32_e32 v131, 0, v131, vcc
	v_cmp_lt_u32_e32 vcc, 15, v142
	v_and_b32_e32 v142, 0xff, v132
	v_mov_b32_e32 v146, v14
	v_cndmask_b32_e32 v130, 0, v130, vcc
	v_pk_fma_f32 v[130:131], v[130:131], v[150:151], v[148:149]
	v_lshlrev_b32_e32 v148, 16, v133
	v_and_b32_e32 v149, 0xffff0000, v133
	v_bfe_u32 v133, v133, 7, 9
	v_cvt_f32_i32_sdwa v151, sext(v143) dst_sel:DWORD dst_unused:UNUSED_PAD src0_sel:BYTE_3
	v_cvt_f32_i32_sdwa v150, sext(v143) dst_sel:DWORD dst_unused:UNUSED_PAD src0_sel:BYTE_2
	v_and_b32_e32 v143, 0xff, v133
	v_lshl_add_u32 v133, v142, 23, v233
	v_lshl_add_u32 v132, v143, 23, v233
	v_pk_mul_f32 v[132:133], v[132:133], s[34:35] op_sel_hi:[1,0]
	v_cmp_lt_u32_e32 vcc, 15, v142
	v_pk_fma_f32 v[120:121], v[130:131], s[82:83], v[120:121] op_sel_hi:[1,0,1]
	s_waitcnt vmcnt(1)
	v_lshlrev_b32_e32 v130, 16, v136
	v_cndmask_b32_e32 v133, 0, v133, vcc
	v_cmp_lt_u32_e32 vcc, 15, v143
	v_and_b32_e32 v131, 0xffff0000, v136
	v_lshrrev_b32_e32 v142, 23, v136
	v_cndmask_b32_e32 v132, 0, v132, vcc
	v_bfe_u32 v136, v136, 7, 9
	v_pk_fma_f32 v[132:133], v[132:133], v[150:151], v[148:149]
	v_and_b32_e32 v144, 0xff, v142
	v_and_b32_e32 v136, 0xff, v136
	v_pk_fma_f32 v[116:117], v[132:133], s[82:83], v[116:117] op_sel_hi:[1,0,1]
	s_waitcnt vmcnt(0)
	v_cvt_f32_i32_sdwa v133, sext(v140) dst_sel:DWORD dst_unused:UNUSED_PAD src0_sel:BYTE_1
	v_cvt_f32_i32_sdwa v132, sext(v140) dst_sel:DWORD dst_unused:UNUSED_PAD src0_sel:BYTE_0
	v_lshl_add_u32 v143, v144, 23, v233
	v_lshl_add_u32 v142, v136, 23, v233
	v_pk_mul_f32 v[142:143], v[142:143], s[34:35] op_sel_hi:[1,0]
	v_cmp_lt_u32_e32 vcc, 15, v144
	v_mov_b32_e32 v147, v17
	v_mov_b32_e32 v148, v10
	v_cndmask_b32_e32 v143, 0, v143, vcc
	v_cmp_lt_u32_e32 vcc, 15, v136
	v_lshrrev_b32_e32 v136, 23, v138
	v_and_b32_e32 v136, 0xff, v136
	v_cndmask_b32_e32 v142, 0, v142, vcc
	v_pk_fma_f32 v[132:133], v[142:143], v[132:133], v[130:131]
	v_lshlrev_b32_e32 v130, 16, v138
	v_and_b32_e32 v131, 0xffff0000, v138
	v_bfe_u32 v138, v138, 7, 9
	v_and_b32_e32 v138, 0xff, v138
	v_cvt_f32_i32_sdwa v143, sext(v141) dst_sel:DWORD dst_unused:UNUSED_PAD src0_sel:BYTE_1
	v_cvt_f32_i32_sdwa v142, sext(v141) dst_sel:DWORD dst_unused:UNUSED_PAD src0_sel:BYTE_0
	v_lshl_add_u32 v145, v136, 23, v233
	v_lshl_add_u32 v144, v138, 23, v233
	v_pk_mul_f32 v[144:145], v[144:145], s[34:35] op_sel_hi:[1,0]
	v_cmp_lt_u32_e32 vcc, 15, v136
	v_lshrrev_b32_e32 v136, 23, v137
	v_mov_b32_e32 v149, v13
	v_cndmask_b32_e32 v145, 0, v145, vcc
	v_cmp_lt_u32_e32 vcc, 15, v138
	v_and_b32_e32 v138, 0xff, v136
	v_add_f32_e32 v151, v8, v9
	v_cndmask_b32_e32 v144, 0, v144, vcc
	v_pk_fma_f32 v[142:143], v[144:145], v[142:143], v[130:131]
	v_lshlrev_b32_e32 v130, 16, v137
	v_and_b32_e32 v131, 0xffff0000, v137
	v_bfe_u32 v137, v137, 7, 9
	v_cvt_f32_i32_sdwa v145, sext(v140) dst_sel:DWORD dst_unused:UNUSED_PAD src0_sel:BYTE_3
	v_cvt_f32_i32_sdwa v144, sext(v140) dst_sel:DWORD dst_unused:UNUSED_PAD src0_sel:BYTE_2
	v_and_b32_e32 v140, 0xff, v137
	v_lshl_add_u32 v137, v138, 23, v233
	v_lshl_add_u32 v136, v140, 23, v233
	v_pk_mul_f32 v[136:137], v[136:137], s[34:35] op_sel_hi:[1,0]
	v_cmp_lt_u32_e32 vcc, 15, v138
	v_lshrrev_b32_e32 v138, 23, v139
	v_mov_b32_e32 v150, v3
	v_cndmask_b32_e32 v137, 0, v137, vcc
	v_cmp_lt_u32_e32 vcc, 15, v140
	v_and_b32_e32 v140, 0xff, v138
	v_pk_fma_f32 v[122:123], v[132:133], s[82:83], v[122:123] op_sel_hi:[1,0,1]
	v_cndmask_b32_e32 v136, 0, v136, vcc
	v_pk_fma_f32 v[130:131], v[136:137], v[144:145], v[130:131]
	v_lshlrev_b32_e32 v136, 16, v139
	v_and_b32_e32 v137, 0xffff0000, v139
	v_bfe_u32 v139, v139, 7, 9
	v_and_b32_e32 v152, 0xff, v139
	v_cvt_f32_i32_sdwa v145, sext(v141) dst_sel:DWORD dst_unused:UNUSED_PAD src0_sel:BYTE_3
	v_cvt_f32_i32_sdwa v144, sext(v141) dst_sel:DWORD dst_unused:UNUSED_PAD src0_sel:BYTE_2
	v_lshl_add_u32 v139, v140, 23, v233
	v_lshl_add_u32 v138, v152, 23, v233
	v_and_b32_e32 v141, 64, v232
	v_pk_mul_f32 v[138:139], v[138:139], s[34:35] op_sel_hi:[1,0]
	v_cmp_lt_u32_e32 vcc, 15, v140
	v_xor_b32_e32 v140, 16, v232
	v_add_u32_e32 v153, 64, v141
	v_cndmask_b32_e32 v139, 0, v139, vcc
	v_cmp_lt_i32_e32 vcc, v140, v153
	v_mov_b32_e32 v141, v16
	v_pk_fma_f32 v[124:125], v[130:131], s[82:83], v[124:125] op_sel_hi:[1,0,1]
	v_cndmask_b32_e32 v140, v232, v140, vcc
	v_lshlrev_b32_e32 v218, 2, v140
	v_mov_b32_e32 v140, v15
	v_pk_add_f32 v[140:141], v[140:141], v[146:147]
	v_mov_b32_e32 v146, v11
	v_mov_b32_e32 v147, v12
	v_pk_add_f32 v[146:147], v[146:147], v[148:149]
	v_add_f32_e32 v140, v140, v141
	v_pk_add_f32 v[146:147], v[146:147], v[146:147] op_sel_hi:[0,1]
	v_add_f32_e32 v141, 0, v140
	v_add_f32_e32 v149, v6, v7
	v_mov_b32_e32 v148, v2
	v_mov_b32_e32 v146, v4
	v_mov_b32_e32 v140, v5
	v_pk_add_f32 v[148:149], v[148:149], v[150:151]
	v_pk_add_f32 v[140:141], v[146:147], v[140:141]
	v_xor_b32_e32 v146, 32, v232
	v_pk_add_f32 v[140:141], v[148:149], v[140:141]
	v_cmp_lt_i32_e32 vcc, v146, v153
	v_add_f32_e32 v140, v140, v141
	ds_bpermute_b32 v141, v218, v140
	v_cndmask_b32_e32 v146, v232, v146, vcc
	v_lshlrev_b32_e32 v219, 2, v146
	v_cmp_lt_u32_e32 vcc, 15, v152
	v_pk_fma_f32 v[126:127], v[142:143], s[82:83], v[126:127] op_sel_hi:[1,0,1]
	s_waitcnt lgkmcnt(0)
	v_add_f32_e32 v140, v140, v141
	ds_bpermute_b32 v141, v219, v140
	v_cndmask_b32_e32 v138, 0, v138, vcc
	v_pk_fma_f32 v[136:137], v[138:139], v[144:145], v[136:137]
	v_cmp_eq_u32_e32 vcc, 0, v134
	v_pk_fma_f32 v[128:129], v[136:137], s[82:83], v[128:129] op_sel_hi:[1,0,1]
	s_waitcnt lgkmcnt(0)
	v_add_f32_e32 v131, v140, v141
	v_fmamk_f32 v138, v131, 0xbc800000, v17
	v_fmamk_f32 v140, v131, 0xbc800000, v15
	v_fmamk_f32 v130, v131, 0xbc800000, v16
	v_fmamk_f32 v139, v131, 0xbc800000, v14
	v_mul_f32_e32 v140, v140, v140
	v_mul_f32_e32 v138, v138, v138
	v_fmac_f32_e32 v140, v139, v139
	v_fmac_f32_e32 v138, v130, v130
	v_fmamk_f32 v139, v131, 0xbc800000, v13
	v_fmamk_f32 v141, v131, 0xbc800000, v11
	v_add_f32_e32 v130, v140, v138
	v_fmamk_f32 v138, v131, 0xbc800000, v12
	v_fmamk_f32 v140, v131, 0xbc800000, v10
	v_mul_f32_e32 v141, v141, v141
	v_mul_f32_e32 v139, v139, v139
	v_fmac_f32_e32 v141, v140, v140
	v_fmac_f32_e32 v139, v138, v138
	v_add_f32_e32 v138, v141, v139
	v_fmamk_f32 v139, v131, 0xbc800000, v9
	v_fmamk_f32 v141, v131, 0xbc800000, v7
	v_add_f32_e32 v130, v130, v138
	v_fmamk_f32 v138, v131, 0xbc800000, v8
	v_fmamk_f32 v140, v131, 0xbc800000, v6
	v_mul_f32_e32 v141, v141, v141
	v_mul_f32_e32 v139, v139, v139
	v_fmac_f32_e32 v141, v140, v140
	v_fmac_f32_e32 v139, v138, v138
	v_add_f32_e32 v138, v141, v139
	v_fmamk_f32 v139, v131, 0xbc800000, v5
	v_fmamk_f32 v141, v131, 0xbc800000, v3
	v_add_f32_e32 v130, v138, v130
	v_fmamk_f32 v138, v131, 0xbc800000, v4
	v_fmamk_f32 v140, v131, 0xbc800000, v2
	v_mul_f32_e32 v141, v141, v141
	v_mul_f32_e32 v139, v139, v139
	v_fmac_f32_e32 v141, v140, v140
	v_fmac_f32_e32 v139, v138, v138
	v_add_f32_e32 v138, v141, v139
	v_add_f32_e32 v130, v138, v130
	ds_bpermute_b32 v138, v218, v130
	s_waitcnt lgkmcnt(0)
	v_add_f32_e32 v132, v130, v138
	ds_bpermute_b32 v133, v219, v132
	v_lshl_add_u32 v130, v214, 5, s68
	s_and_saveexec_b64 s[4:5], vcc
	s_cbranch_execz .LBB0_822
	v_mul_f32_e32 v136, 0x3c800000, v131
	s_waitcnt lgkmcnt(0)
	v_add_f32_e32 v137, v132, v133
	ds_write_b64 v130, v[136:137]

.LBB0_1061:
	v_mov_b32_e32 v132, v192
	v_mov_b32_e32 v133, v191
	s_lshl_b32 s2, s63, 8
	v_add_u32_e32 v200, s50, v133
	s_lshl_b32 s0, s28, 8
	v_add_u32_e32 v174, s2, v200
	s_or_b32 s0, s0, s51
	v_lshl_add_u32 v128, v132, 3, s0
	v_ashrrev_i32_e32 v175, 31, v174
	v_ashrrev_i32_e32 v129, 31, v128
	v_lshlrev_b64 v[130:131], 13, v[174:175]
	v_lshl_add_u64 v[134:135], s[10:11], 0, v[130:131]
	v_lshlrev_b64 v[130:131], 1, v[128:129]
	v_lshl_add_u64 v[138:139], v[134:135], 0, v[130:131]
	s_mov_b32 s99, 0
	s_mov_b32 s98, 0x20000
	v_lshl_add_u64 v[226:227], v[138:139], 0, s[98:99]
	global_load_dword v228, v[226:227], off
	global_load_dword v229, v[226:227], off offset:256
	s_mov_b32 s98, 0x40000
	v_lshl_add_u64 v[226:227], v[138:139], 0, s[98:99]
	global_load_dword v228, v[226:227], off
	global_load_dword v229, v[226:227], off offset:256
	s_mov_b32 s98, 0x60000
	v_lshl_add_u64 v[226:227], v[138:139], 0, s[98:99]
	global_load_dword v228, v[226:227], off
	global_load_dword v229, v[226:227], off offset:256
	s_mov_b32 s98, 0x100000
	v_lshl_add_u64 v[226:227], v[138:139], 0, s[98:99]
	global_load_dword v228, v[226:227], off
	global_load_dword v229, v[226:227], off offset:256
	s_mov_b32 s98, 0x120000
	v_lshl_add_u64 v[226:227], v[138:139], 0, s[98:99]
	global_load_dword v228, v[226:227], off
	global_load_dword v229, v[226:227], off offset:256
	s_mov_b32 s98, 0x140000
	v_lshl_add_u64 v[226:227], v[138:139], 0, s[98:99]
	global_load_dword v228, v[226:227], off
	global_load_dword v229, v[226:227], off offset:256
	s_mov_b32 s98, 0x160000
	v_lshl_add_u64 v[226:227], v[138:139], 0, s[98:99]
	global_load_dword v228, v[226:227], off
	global_load_dword v229, v[226:227], off offset:256
	global_load_dwordx4 v[134:137], v[138:139], off
	s_nop 0
	global_load_dwordx4 v[138:141], v[138:139], off offset:256
	v_add_u32_e32 v176, 16, v174
	v_ashrrev_i32_e32 v177, 31, v176
	v_lshlrev_b64 v[142:143], 13, v[176:177]
	v_lshl_add_u64 v[142:143], s[10:11], 0, v[142:143]
	v_lshl_add_u64 v[142:143], v[142:143], 0, v[130:131]
	v_add_u32_e32 v172, 32, v174
	v_ashrrev_i32_e32 v173, 31, v172
	v_add_u32_e32 v178, 48, v174
	v_ashrrev_i32_e32 v179, 31, v178
	v_add_u32_e32 v180, 0x80, v174
	v_ashrrev_i32_e32 v181, 31, v180
	v_add_u32_e32 v182, 0x90, v174
	v_ashrrev_i32_e32 v183, 31, v182
	v_add_u32_e32 v184, 0xa0, v174
	v_ashrrev_i32_e32 v185, 31, v184
	v_add_u32_e32 v186, 0xb0, v174
	v_ashrrev_i32_e32 v187, 31, v186
	v_cmp_eq_u32_e32 vcc, 0, v132
	s_waitcnt vmcnt(0)
	v_cvt_f32_i32_sdwa v145, sext(v135) dst_sel:DWORD dst_unused:UNUSED_PAD src0_sel:WORD_1
	v_cvt_f32_i32_sdwa v144, sext(v135) dst_sel:DWORD dst_unused:UNUSED_PAD src0_sel:WORD_0
	v_cvt_f32_i32_sdwa v135, sext(v134) dst_sel:DWORD dst_unused:UNUSED_PAD src0_sel:WORD_1
	v_cvt_f32_i32_sdwa v134, sext(v134) dst_sel:DWORD dst_unused:UNUSED_PAD src0_sel:WORD_0
	v_cvt_f32_i32_sdwa v147, sext(v137) dst_sel:DWORD dst_unused:UNUSED_PAD src0_sel:WORD_1
	v_cvt_f32_i32_sdwa v146, sext(v137) dst_sel:DWORD dst_unused:UNUSED_PAD src0_sel:WORD_0
	v_cvt_f32_i32_sdwa v137, sext(v136) dst_sel:DWORD dst_unused:UNUSED_PAD src0_sel:WORD_1
	v_cvt_f32_i32_sdwa v136, sext(v136) dst_sel:DWORD dst_unused:UNUSED_PAD src0_sel:WORD_0
	v_cvt_f32_i32_sdwa v149, sext(v139) dst_sel:DWORD dst_unused:UNUSED_PAD src0_sel:WORD_1
	v_cvt_f32_i32_sdwa v148, sext(v139) dst_sel:DWORD dst_unused:UNUSED_PAD src0_sel:WORD_0
	v_cvt_f32_i32_sdwa v139, sext(v138) dst_sel:DWORD dst_unused:UNUSED_PAD src0_sel:WORD_1
	v_cvt_f32_i32_sdwa v138, sext(v138) dst_sel:DWORD dst_unused:UNUSED_PAD src0_sel:WORD_0
	v_cvt_f32_i32_sdwa v151, sext(v141) dst_sel:DWORD dst_unused:UNUSED_PAD src0_sel:WORD_1
	v_cvt_f32_i32_sdwa v150, sext(v141) dst_sel:DWORD dst_unused:UNUSED_PAD src0_sel:WORD_0
	v_cvt_f32_i32_sdwa v141, sext(v140) dst_sel:DWORD dst_unused:UNUSED_PAD src0_sel:WORD_1
	v_cvt_f32_i32_sdwa v140, sext(v140) dst_sel:DWORD dst_unused:UNUSED_PAD src0_sel:WORD_0
	v_pk_mul_f32 v[134:135], v[134:135], s[24:25] op_sel_hi:[1,0]
	v_pk_mul_f32 v[144:145], v[144:145], s[24:25] op_sel_hi:[1,0]
	v_pk_mul_f32 v[136:137], v[136:137], s[24:25] op_sel_hi:[1,0]
	v_pk_mul_f32 v[146:147], v[146:147], s[24:25] op_sel_hi:[1,0]
	v_pk_mul_f32 v[138:139], v[138:139], s[24:25] op_sel_hi:[1,0]
	v_pk_mul_f32 v[148:149], v[148:149], s[24:25] op_sel_hi:[1,0]
	v_pk_mul_f32 v[140:141], v[140:141], s[24:25] op_sel_hi:[1,0]
	v_pk_mul_f32 v[150:151], v[150:151], s[24:25] op_sel_hi:[1,0]
	v_pk_fma_f32 v[14:15], v[144:145], s[26:27], v[14:15] op_sel_hi:[1,0,1]
	v_pk_fma_f32 v[12:13], v[134:135], s[26:27], v[12:13] op_sel_hi:[1,0,1]
	v_pk_fma_f32 v[10:11], v[146:147], s[26:27], v[10:11] op_sel_hi:[1,0,1]
	v_pk_fma_f32 v[8:9], v[136:137], s[26:27], v[8:9] op_sel_hi:[1,0,1]
	v_pk_fma_f32 v[6:7], v[148:149], s[26:27], v[6:7] op_sel_hi:[1,0,1]
	v_pk_fma_f32 v[4:5], v[138:139], s[26:27], v[4:5] op_sel_hi:[1,0,1]
	v_pk_fma_f32 v[2:3], v[150:151], s[26:27], v[2:3] op_sel_hi:[1,0,1]
	v_pk_fma_f32 v[0:1], v[140:141], s[26:27], v[0:1] op_sel_hi:[1,0,1]
	s_nop 0
	global_load_dwordx4 v[134:137], v[142:143], off
	global_load_dwordx4 v[138:141], v[142:143], off offset:256
	v_lshlrev_b64 v[142:143], 13, v[172:173]
	v_lshl_add_u64 v[142:143], s[10:11], 0, v[142:143]
	v_lshl_add_u64 v[142:143], v[142:143], 0, v[130:131]
	s_waitcnt vmcnt(1)
	v_cvt_f32_i32_sdwa v145, sext(v135) dst_sel:DWORD dst_unused:UNUSED_PAD src0_sel:WORD_1
	v_cvt_f32_i32_sdwa v144, sext(v135) dst_sel:DWORD dst_unused:UNUSED_PAD src0_sel:WORD_0
	v_cvt_f32_i32_sdwa v135, sext(v134) dst_sel:DWORD dst_unused:UNUSED_PAD src0_sel:WORD_1
	v_cvt_f32_i32_sdwa v134, sext(v134) dst_sel:DWORD dst_unused:UNUSED_PAD src0_sel:WORD_0
	v_cvt_f32_i32_sdwa v147, sext(v137) dst_sel:DWORD dst_unused:UNUSED_PAD src0_sel:WORD_1
	v_cvt_f32_i32_sdwa v146, sext(v137) dst_sel:DWORD dst_unused:UNUSED_PAD src0_sel:WORD_0
	v_cvt_f32_i32_sdwa v137, sext(v136) dst_sel:DWORD dst_unused:UNUSED_PAD src0_sel:WORD_1
	v_cvt_f32_i32_sdwa v136, sext(v136) dst_sel:DWORD dst_unused:UNUSED_PAD src0_sel:WORD_0
	s_waitcnt vmcnt(0)
	v_cvt_f32_i32_sdwa v149, sext(v139) dst_sel:DWORD dst_unused:UNUSED_PAD src0_sel:WORD_1
	v_cvt_f32_i32_sdwa v148, sext(v139) dst_sel:DWORD dst_unused:UNUSED_PAD src0_sel:WORD_0
	v_cvt_f32_i32_sdwa v139, sext(v138) dst_sel:DWORD dst_unused:UNUSED_PAD src0_sel:WORD_1
	v_cvt_f32_i32_sdwa v138, sext(v138) dst_sel:DWORD dst_unused:UNUSED_PAD src0_sel:WORD_0
	v_cvt_f32_i32_sdwa v151, sext(v141) dst_sel:DWORD dst_unused:UNUSED_PAD src0_sel:WORD_1
	v_cvt_f32_i32_sdwa v150, sext(v141) dst_sel:DWORD dst_unused:UNUSED_PAD src0_sel:WORD_0
	v_cvt_f32_i32_sdwa v141, sext(v140) dst_sel:DWORD dst_unused:UNUSED_PAD src0_sel:WORD_1
	v_cvt_f32_i32_sdwa v140, sext(v140) dst_sel:DWORD dst_unused:UNUSED_PAD src0_sel:WORD_0
	v_pk_mul_f32 v[134:135], v[134:135], s[24:25] op_sel_hi:[1,0]
	v_pk_mul_f32 v[144:145], v[144:145], s[24:25] op_sel_hi:[1,0]
	v_pk_mul_f32 v[136:137], v[136:137], s[24:25] op_sel_hi:[1,0]
	v_pk_mul_f32 v[146:147], v[146:147], s[24:25] op_sel_hi:[1,0]
	v_pk_mul_f32 v[138:139], v[138:139], s[24:25] op_sel_hi:[1,0]
	v_pk_mul_f32 v[148:149], v[148:149], s[24:25] op_sel_hi:[1,0]
	v_pk_mul_f32 v[140:141], v[140:141], s[24:25] op_sel_hi:[1,0]
	v_pk_mul_f32 v[150:151], v[150:151], s[24:25] op_sel_hi:[1,0]
	v_pk_fma_f32 v[38:39], v[144:145], s[26:27], v[38:39] op_sel_hi:[1,0,1]
	v_pk_fma_f32 v[36:37], v[134:135], s[26:27], v[36:37] op_sel_hi:[1,0,1]
	v_pk_fma_f32 v[34:35], v[146:147], s[26:27], v[34:35] op_sel_hi:[1,0,1]
	v_pk_fma_f32 v[32:33], v[136:137], s[26:27], v[32:33] op_sel_hi:[1,0,1]
	v_pk_fma_f32 v[26:27], v[148:149], s[26:27], v[26:27] op_sel_hi:[1,0,1]
	v_pk_fma_f32 v[24:25], v[138:139], s[26:27], v[24:25] op_sel_hi:[1,0,1]
	v_pk_fma_f32 v[18:19], v[150:151], s[26:27], v[18:19] op_sel_hi:[1,0,1]
	v_pk_fma_f32 v[16:17], v[140:141], s[26:27], v[16:17] op_sel_hi:[1,0,1]
	s_nop 0
	global_load_dwordx4 v[134:137], v[142:143], off
	global_load_dwordx4 v[138:141], v[142:143], off offset:256
	v_lshlrev_b64 v[142:143], 13, v[178:179]
	v_lshl_add_u64 v[142:143], s[10:11], 0, v[142:143]
	v_lshl_add_u64 v[142:143], v[142:143], 0, v[130:131]
	s_waitcnt vmcnt(1)
	v_cvt_f32_i32_sdwa v145, sext(v135) dst_sel:DWORD dst_unused:UNUSED_PAD src0_sel:WORD_1
	v_cvt_f32_i32_sdwa v144, sext(v135) dst_sel:DWORD dst_unused:UNUSED_PAD src0_sel:WORD_0
	v_cvt_f32_i32_sdwa v135, sext(v134) dst_sel:DWORD dst_unused:UNUSED_PAD src0_sel:WORD_1
	v_cvt_f32_i32_sdwa v134, sext(v134) dst_sel:DWORD dst_unused:UNUSED_PAD src0_sel:WORD_0
	v_cvt_f32_i32_sdwa v147, sext(v137) dst_sel:DWORD dst_unused:UNUSED_PAD src0_sel:WORD_1
	v_cvt_f32_i32_sdwa v146, sext(v137) dst_sel:DWORD dst_unused:UNUSED_PAD src0_sel:WORD_0
	v_cvt_f32_i32_sdwa v137, sext(v136) dst_sel:DWORD dst_unused:UNUSED_PAD src0_sel:WORD_1
	v_cvt_f32_i32_sdwa v136, sext(v136) dst_sel:DWORD dst_unused:UNUSED_PAD src0_sel:WORD_0
	s_waitcnt vmcnt(0)
	v_cvt_f32_i32_sdwa v149, sext(v139) dst_sel:DWORD dst_unused:UNUSED_PAD src0_sel:WORD_1
	v_cvt_f32_i32_sdwa v148, sext(v139) dst_sel:DWORD dst_unused:UNUSED_PAD src0_sel:WORD_0
	v_cvt_f32_i32_sdwa v139, sext(v138) dst_sel:DWORD dst_unused:UNUSED_PAD src0_sel:WORD_1
	v_cvt_f32_i32_sdwa v138, sext(v138) dst_sel:DWORD dst_unused:UNUSED_PAD src0_sel:WORD_0
	v_cvt_f32_i32_sdwa v151, sext(v141) dst_sel:DWORD dst_unused:UNUSED_PAD src0_sel:WORD_1
	v_cvt_f32_i32_sdwa v150, sext(v141) dst_sel:DWORD dst_unused:UNUSED_PAD src0_sel:WORD_0
	v_cvt_f32_i32_sdwa v141, sext(v140) dst_sel:DWORD dst_unused:UNUSED_PAD src0_sel:WORD_1
	v_cvt_f32_i32_sdwa v140, sext(v140) dst_sel:DWORD dst_unused:UNUSED_PAD src0_sel:WORD_0
	v_pk_mul_f32 v[134:135], v[134:135], s[24:25] op_sel_hi:[1,0]
	v_pk_mul_f32 v[144:145], v[144:145], s[24:25] op_sel_hi:[1,0]
	v_pk_mul_f32 v[136:137], v[136:137], s[24:25] op_sel_hi:[1,0]
	v_pk_mul_f32 v[146:147], v[146:147], s[24:25] op_sel_hi:[1,0]
	v_pk_mul_f32 v[138:139], v[138:139], s[24:25] op_sel_hi:[1,0]
	v_pk_mul_f32 v[148:149], v[148:149], s[24:25] op_sel_hi:[1,0]
	v_pk_mul_f32 v[140:141], v[140:141], s[24:25] op_sel_hi:[1,0]
	v_pk_mul_f32 v[150:151], v[150:151], s[24:25] op_sel_hi:[1,0]
	v_pk_fma_f32 v[46:47], v[144:145], s[26:27], v[46:47] op_sel_hi:[1,0,1]
	v_pk_fma_f32 v[44:45], v[134:135], s[26:27], v[44:45] op_sel_hi:[1,0,1]
	v_pk_fma_f32 v[42:43], v[146:147], s[26:27], v[42:43] op_sel_hi:[1,0,1]
	v_pk_fma_f32 v[40:41], v[136:137], s[26:27], v[40:41] op_sel_hi:[1,0,1]
	v_pk_fma_f32 v[30:31], v[148:149], s[26:27], v[30:31] op_sel_hi:[1,0,1]
	v_pk_fma_f32 v[28:29], v[138:139], s[26:27], v[28:29] op_sel_hi:[1,0,1]
	v_pk_fma_f32 v[22:23], v[150:151], s[26:27], v[22:23] op_sel_hi:[1,0,1]
	v_pk_fma_f32 v[20:21], v[140:141], s[26:27], v[20:21] op_sel_hi:[1,0,1]
	s_nop 0
	global_load_dwordx4 v[134:137], v[142:143], off
	global_load_dwordx4 v[138:141], v[142:143], off offset:256
	v_lshlrev_b64 v[142:143], 13, v[180:181]
	v_lshl_add_u64 v[142:143], s[10:11], 0, v[142:143]
	v_lshl_add_u64 v[142:143], v[142:143], 0, v[130:131]
	s_waitcnt vmcnt(1)
	v_cvt_f32_i32_sdwa v145, sext(v135) dst_sel:DWORD dst_unused:UNUSED_PAD src0_sel:WORD_1
	v_cvt_f32_i32_sdwa v144, sext(v135) dst_sel:DWORD dst_unused:UNUSED_PAD src0_sel:WORD_0
	v_cvt_f32_i32_sdwa v135, sext(v134) dst_sel:DWORD dst_unused:UNUSED_PAD src0_sel:WORD_1
	v_cvt_f32_i32_sdwa v134, sext(v134) dst_sel:DWORD dst_unused:UNUSED_PAD src0_sel:WORD_0
	v_cvt_f32_i32_sdwa v147, sext(v137) dst_sel:DWORD dst_unused:UNUSED_PAD src0_sel:WORD_1
	v_cvt_f32_i32_sdwa v146, sext(v137) dst_sel:DWORD dst_unused:UNUSED_PAD src0_sel:WORD_0
	v_cvt_f32_i32_sdwa v137, sext(v136) dst_sel:DWORD dst_unused:UNUSED_PAD src0_sel:WORD_1
	v_cvt_f32_i32_sdwa v136, sext(v136) dst_sel:DWORD dst_unused:UNUSED_PAD src0_sel:WORD_0
	s_waitcnt vmcnt(0)
	v_cvt_f32_i32_sdwa v149, sext(v139) dst_sel:DWORD dst_unused:UNUSED_PAD src0_sel:WORD_1
	v_cvt_f32_i32_sdwa v148, sext(v139) dst_sel:DWORD dst_unused:UNUSED_PAD src0_sel:WORD_0
	v_cvt_f32_i32_sdwa v139, sext(v138) dst_sel:DWORD dst_unused:UNUSED_PAD src0_sel:WORD_1
	v_cvt_f32_i32_sdwa v138, sext(v138) dst_sel:DWORD dst_unused:UNUSED_PAD src0_sel:WORD_0
	v_cvt_f32_i32_sdwa v151, sext(v141) dst_sel:DWORD dst_unused:UNUSED_PAD src0_sel:WORD_1
	v_cvt_f32_i32_sdwa v150, sext(v141) dst_sel:DWORD dst_unused:UNUSED_PAD src0_sel:WORD_0
	v_cvt_f32_i32_sdwa v141, sext(v140) dst_sel:DWORD dst_unused:UNUSED_PAD src0_sel:WORD_1
	v_cvt_f32_i32_sdwa v140, sext(v140) dst_sel:DWORD dst_unused:UNUSED_PAD src0_sel:WORD_0
	v_pk_mul_f32 v[134:135], v[134:135], s[24:25] op_sel_hi:[1,0]
	v_pk_mul_f32 v[144:145], v[144:145], s[24:25] op_sel_hi:[1,0]
	v_pk_mul_f32 v[136:137], v[136:137], s[24:25] op_sel_hi:[1,0]
	v_pk_mul_f32 v[146:147], v[146:147], s[24:25] op_sel_hi:[1,0]
	v_pk_mul_f32 v[138:139], v[138:139], s[24:25] op_sel_hi:[1,0]
	v_pk_mul_f32 v[148:149], v[148:149], s[24:25] op_sel_hi:[1,0]
	v_pk_mul_f32 v[140:141], v[140:141], s[24:25] op_sel_hi:[1,0]
	v_pk_mul_f32 v[150:151], v[150:151], s[24:25] op_sel_hi:[1,0]
	v_pk_fma_f32 v[66:67], v[144:145], s[26:27], v[66:67] op_sel_hi:[1,0,1]
	v_pk_fma_f32 v[64:65], v[134:135], s[26:27], v[64:65] op_sel_hi:[1,0,1]
	v_pk_fma_f32 v[58:59], v[146:147], s[26:27], v[58:59] op_sel_hi:[1,0,1]
	v_pk_fma_f32 v[56:57], v[136:137], s[26:27], v[56:57] op_sel_hi:[1,0,1]
	v_pk_fma_f32 v[54:55], v[148:149], s[26:27], v[54:55] op_sel_hi:[1,0,1]
	v_pk_fma_f32 v[52:53], v[138:139], s[26:27], v[52:53] op_sel_hi:[1,0,1]
	v_pk_fma_f32 v[50:51], v[150:151], s[26:27], v[50:51] op_sel_hi:[1,0,1]
	v_pk_fma_f32 v[48:49], v[140:141], s[26:27], v[48:49] op_sel_hi:[1,0,1]
	s_nop 0
	global_load_dwordx4 v[134:137], v[142:143], off
	global_load_dwordx4 v[138:141], v[142:143], off offset:256
	v_lshlrev_b64 v[142:143], 13, v[182:183]
	v_lshl_add_u64 v[142:143], s[10:11], 0, v[142:143]
	v_lshl_add_u64 v[142:143], v[142:143], 0, v[130:131]
	s_waitcnt vmcnt(1)
	v_cvt_f32_i32_sdwa v145, sext(v135) dst_sel:DWORD dst_unused:UNUSED_PAD src0_sel:WORD_1
	v_cvt_f32_i32_sdwa v144, sext(v135) dst_sel:DWORD dst_unused:UNUSED_PAD src0_sel:WORD_0
	v_cvt_f32_i32_sdwa v135, sext(v134) dst_sel:DWORD dst_unused:UNUSED_PAD src0_sel:WORD_1
	v_cvt_f32_i32_sdwa v134, sext(v134) dst_sel:DWORD dst_unused:UNUSED_PAD src0_sel:WORD_0
	v_cvt_f32_i32_sdwa v147, sext(v137) dst_sel:DWORD dst_unused:UNUSED_PAD src0_sel:WORD_1
	v_cvt_f32_i32_sdwa v146, sext(v137) dst_sel:DWORD dst_unused:UNUSED_PAD src0_sel:WORD_0
	v_cvt_f32_i32_sdwa v137, sext(v136) dst_sel:DWORD dst_unused:UNUSED_PAD src0_sel:WORD_1
	v_cvt_f32_i32_sdwa v136, sext(v136) dst_sel:DWORD dst_unused:UNUSED_PAD src0_sel:WORD_0
	s_waitcnt vmcnt(0)
	v_cvt_f32_i32_sdwa v149, sext(v139) dst_sel:DWORD dst_unused:UNUSED_PAD src0_sel:WORD_1
	v_cvt_f32_i32_sdwa v148, sext(v139) dst_sel:DWORD dst_unused:UNUSED_PAD src0_sel:WORD_0
	v_cvt_f32_i32_sdwa v139, sext(v138) dst_sel:DWORD dst_unused:UNUSED_PAD src0_sel:WORD_1
	v_cvt_f32_i32_sdwa v138, sext(v138) dst_sel:DWORD dst_unused:UNUSED_PAD src0_sel:WORD_0
	v_cvt_f32_i32_sdwa v151, sext(v141) dst_sel:DWORD dst_unused:UNUSED_PAD src0_sel:WORD_1
	v_cvt_f32_i32_sdwa v150, sext(v141) dst_sel:DWORD dst_unused:UNUSED_PAD src0_sel:WORD_0
	v_cvt_f32_i32_sdwa v141, sext(v140) dst_sel:DWORD dst_unused:UNUSED_PAD src0_sel:WORD_1
	v_cvt_f32_i32_sdwa v140, sext(v140) dst_sel:DWORD dst_unused:UNUSED_PAD src0_sel:WORD_0
	v_pk_mul_f32 v[134:135], v[134:135], s[24:25] op_sel_hi:[1,0]
	v_pk_mul_f32 v[144:145], v[144:145], s[24:25] op_sel_hi:[1,0]
	v_pk_mul_f32 v[136:137], v[136:137], s[24:25] op_sel_hi:[1,0]
	v_pk_mul_f32 v[146:147], v[146:147], s[24:25] op_sel_hi:[1,0]
	v_pk_mul_f32 v[138:139], v[138:139], s[24:25] op_sel_hi:[1,0]
	v_pk_mul_f32 v[148:149], v[148:149], s[24:25] op_sel_hi:[1,0]
	v_pk_mul_f32 v[140:141], v[140:141], s[24:25] op_sel_hi:[1,0]
	v_pk_mul_f32 v[150:151], v[150:151], s[24:25] op_sel_hi:[1,0]
	v_pk_fma_f32 v[78:79], v[144:145], s[26:27], v[78:79] op_sel_hi:[1,0,1]
	v_pk_fma_f32 v[76:77], v[134:135], s[26:27], v[76:77] op_sel_hi:[1,0,1]
	v_pk_fma_f32 v[74:75], v[146:147], s[26:27], v[74:75] op_sel_hi:[1,0,1]
	v_pk_fma_f32 v[72:73], v[136:137], s[26:27], v[72:73] op_sel_hi:[1,0,1]
	v_pk_fma_f32 v[70:71], v[148:149], s[26:27], v[70:71] op_sel_hi:[1,0,1]
	v_pk_fma_f32 v[68:69], v[138:139], s[26:27], v[68:69] op_sel_hi:[1,0,1]
	v_pk_fma_f32 v[62:63], v[150:151], s[26:27], v[62:63] op_sel_hi:[1,0,1]
	v_pk_fma_f32 v[60:61], v[140:141], s[26:27], v[60:61] op_sel_hi:[1,0,1]
	s_nop 0
	global_load_dwordx4 v[134:137], v[142:143], off
	global_load_dwordx4 v[138:141], v[142:143], off offset:256
	v_lshlrev_b64 v[142:143], 13, v[184:185]
	v_lshl_add_u64 v[142:143], s[10:11], 0, v[142:143]
	v_lshl_add_u64 v[142:143], v[142:143], 0, v[130:131]
	s_waitcnt vmcnt(1)
	v_cvt_f32_i32_sdwa v145, sext(v135) dst_sel:DWORD dst_unused:UNUSED_PAD src0_sel:WORD_1
	v_cvt_f32_i32_sdwa v144, sext(v135) dst_sel:DWORD dst_unused:UNUSED_PAD src0_sel:WORD_0
	v_cvt_f32_i32_sdwa v135, sext(v134) dst_sel:DWORD dst_unused:UNUSED_PAD src0_sel:WORD_1
	v_cvt_f32_i32_sdwa v134, sext(v134) dst_sel:DWORD dst_unused:UNUSED_PAD src0_sel:WORD_0
	v_cvt_f32_i32_sdwa v147, sext(v137) dst_sel:DWORD dst_unused:UNUSED_PAD src0_sel:WORD_1
	v_cvt_f32_i32_sdwa v146, sext(v137) dst_sel:DWORD dst_unused:UNUSED_PAD src0_sel:WORD_0
	v_cvt_f32_i32_sdwa v137, sext(v136) dst_sel:DWORD dst_unused:UNUSED_PAD src0_sel:WORD_1
	v_cvt_f32_i32_sdwa v136, sext(v136) dst_sel:DWORD dst_unused:UNUSED_PAD src0_sel:WORD_0
	s_waitcnt vmcnt(0)
	v_cvt_f32_i32_sdwa v149, sext(v139) dst_sel:DWORD dst_unused:UNUSED_PAD src0_sel:WORD_1
	v_cvt_f32_i32_sdwa v148, sext(v139) dst_sel:DWORD dst_unused:UNUSED_PAD src0_sel:WORD_0
	v_cvt_f32_i32_sdwa v139, sext(v138) dst_sel:DWORD dst_unused:UNUSED_PAD src0_sel:WORD_1
	v_cvt_f32_i32_sdwa v138, sext(v138) dst_sel:DWORD dst_unused:UNUSED_PAD src0_sel:WORD_0
	v_cvt_f32_i32_sdwa v151, sext(v141) dst_sel:DWORD dst_unused:UNUSED_PAD src0_sel:WORD_1
	v_cvt_f32_i32_sdwa v150, sext(v141) dst_sel:DWORD dst_unused:UNUSED_PAD src0_sel:WORD_0
	v_cvt_f32_i32_sdwa v141, sext(v140) dst_sel:DWORD dst_unused:UNUSED_PAD src0_sel:WORD_1
	v_cvt_f32_i32_sdwa v140, sext(v140) dst_sel:DWORD dst_unused:UNUSED_PAD src0_sel:WORD_0
	v_pk_mul_f32 v[134:135], v[134:135], s[24:25] op_sel_hi:[1,0]
	v_pk_mul_f32 v[144:145], v[144:145], s[24:25] op_sel_hi:[1,0]
	v_pk_mul_f32 v[136:137], v[136:137], s[24:25] op_sel_hi:[1,0]
	v_pk_mul_f32 v[146:147], v[146:147], s[24:25] op_sel_hi:[1,0]
	v_pk_mul_f32 v[138:139], v[138:139], s[24:25] op_sel_hi:[1,0]
	v_pk_mul_f32 v[148:149], v[148:149], s[24:25] op_sel_hi:[1,0]
	v_pk_mul_f32 v[140:141], v[140:141], s[24:25] op_sel_hi:[1,0]
	v_pk_mul_f32 v[150:151], v[150:151], s[24:25] op_sel_hi:[1,0]
	v_pk_fma_f32 v[94:95], v[144:145], s[26:27], v[94:95] op_sel_hi:[1,0,1]
	v_pk_fma_f32 v[92:93], v[134:135], s[26:27], v[92:93] op_sel_hi:[1,0,1]
	v_pk_fma_f32 v[90:91], v[146:147], s[26:27], v[90:91] op_sel_hi:[1,0,1]
	v_pk_fma_f32 v[88:89], v[136:137], s[26:27], v[88:89] op_sel_hi:[1,0,1]
	v_pk_fma_f32 v[86:87], v[148:149], s[26:27], v[86:87] op_sel_hi:[1,0,1]
	v_pk_fma_f32 v[84:85], v[138:139], s[26:27], v[84:85] op_sel_hi:[1,0,1]
	v_pk_fma_f32 v[82:83], v[150:151], s[26:27], v[82:83] op_sel_hi:[1,0,1]
	v_pk_fma_f32 v[80:81], v[140:141], s[26:27], v[80:81] op_sel_hi:[1,0,1]
	v_mov_b32_e32 v144, v13
	global_load_dwordx4 v[134:137], v[142:143], off
	global_load_dwordx4 v[138:141], v[142:143], off offset:256
	v_lshlrev_b64 v[142:143], 13, v[186:187]
	v_lshl_add_u64 v[142:143], s[10:11], 0, v[142:143]
	v_lshl_add_u64 v[130:131], v[142:143], 0, v[130:131]
	v_mov_b32_e32 v145, v14
	v_mov_b32_e32 v146, v12
	v_mov_b32_e32 v147, v15
	v_pk_add_f32 v[144:145], v[144:145], v[146:147]
	s_waitcnt vmcnt(1)
	v_cvt_f32_i32_sdwa v143, sext(v135) dst_sel:DWORD dst_unused:UNUSED_PAD src0_sel:WORD_1
	v_cvt_f32_i32_sdwa v142, sext(v135) dst_sel:DWORD dst_unused:UNUSED_PAD src0_sel:WORD_0
	v_cvt_f32_i32_sdwa v135, sext(v134) dst_sel:DWORD dst_unused:UNUSED_PAD src0_sel:WORD_1
	v_cvt_f32_i32_sdwa v134, sext(v134) dst_sel:DWORD dst_unused:UNUSED_PAD src0_sel:WORD_0
	v_cvt_f32_i32_sdwa v149, sext(v137) dst_sel:DWORD dst_unused:UNUSED_PAD src0_sel:WORD_1
	v_cvt_f32_i32_sdwa v148, sext(v137) dst_sel:DWORD dst_unused:UNUSED_PAD src0_sel:WORD_0
	v_cvt_f32_i32_sdwa v137, sext(v136) dst_sel:DWORD dst_unused:UNUSED_PAD src0_sel:WORD_1
	v_cvt_f32_i32_sdwa v136, sext(v136) dst_sel:DWORD dst_unused:UNUSED_PAD src0_sel:WORD_0
	s_waitcnt vmcnt(0)
	v_cvt_f32_i32_sdwa v151, sext(v139) dst_sel:DWORD dst_unused:UNUSED_PAD src0_sel:WORD_1
	v_cvt_f32_i32_sdwa v150, sext(v139) dst_sel:DWORD dst_unused:UNUSED_PAD src0_sel:WORD_0
	v_cvt_f32_i32_sdwa v139, sext(v138) dst_sel:DWORD dst_unused:UNUSED_PAD src0_sel:WORD_1
	v_cvt_f32_i32_sdwa v138, sext(v138) dst_sel:DWORD dst_unused:UNUSED_PAD src0_sel:WORD_0
	v_cvt_f32_i32_sdwa v153, sext(v141) dst_sel:DWORD dst_unused:UNUSED_PAD src0_sel:WORD_1
	v_cvt_f32_i32_sdwa v152, sext(v141) dst_sel:DWORD dst_unused:UNUSED_PAD src0_sel:WORD_0
	v_cvt_f32_i32_sdwa v141, sext(v140) dst_sel:DWORD dst_unused:UNUSED_PAD src0_sel:WORD_1
	v_cvt_f32_i32_sdwa v140, sext(v140) dst_sel:DWORD dst_unused:UNUSED_PAD src0_sel:WORD_0
	v_pk_mul_f32 v[134:135], v[134:135], s[24:25] op_sel_hi:[1,0]
	v_pk_mul_f32 v[142:143], v[142:143], s[24:25] op_sel_hi:[1,0]
	v_pk_mul_f32 v[136:137], v[136:137], s[24:25] op_sel_hi:[1,0]
	v_pk_mul_f32 v[148:149], v[148:149], s[24:25] op_sel_hi:[1,0]
	v_pk_mul_f32 v[138:139], v[138:139], s[24:25] op_sel_hi:[1,0]
	v_pk_mul_f32 v[150:151], v[150:151], s[24:25] op_sel_hi:[1,0]
	v_pk_mul_f32 v[140:141], v[140:141], s[24:25] op_sel_hi:[1,0]
	v_pk_mul_f32 v[152:153], v[152:153], s[24:25] op_sel_hi:[1,0]
	v_pk_fma_f32 v[110:111], v[142:143], s[26:27], v[110:111] op_sel_hi:[1,0,1]
	v_pk_fma_f32 v[108:109], v[134:135], s[26:27], v[108:109] op_sel_hi:[1,0,1]
	v_pk_fma_f32 v[106:107], v[148:149], s[26:27], v[106:107] op_sel_hi:[1,0,1]
	v_pk_fma_f32 v[104:105], v[136:137], s[26:27], v[104:105] op_sel_hi:[1,0,1]
	v_pk_fma_f32 v[102:103], v[150:151], s[26:27], v[102:103] op_sel_hi:[1,0,1]
	v_pk_fma_f32 v[100:101], v[138:139], s[26:27], v[100:101] op_sel_hi:[1,0,1]
	v_pk_fma_f32 v[98:99], v[152:153], s[26:27], v[98:99] op_sel_hi:[1,0,1]
	v_pk_fma_f32 v[96:97], v[140:141], s[26:27], v[96:97] op_sel_hi:[1,0,1]
	v_mov_b32_e32 v134, v9
	global_load_dwordx4 v[136:139], v[130:131], off
	global_load_dwordx4 v[140:143], v[130:131], off offset:256
	v_mov_b32_e32 v135, v10
	v_mov_b32_e32 v148, v8
	v_mov_b32_e32 v149, v11
	v_pk_add_f32 v[134:135], v[134:135], v[148:149]
	v_add_f32_e32 v131, v144, v145
	v_pk_add_f32 v[134:135], v[134:135], v[134:135] op_sel_hi:[0,1]
	v_add_f32_e32 v151, v4, v5
	v_add_f32_e32 v153, v6, v7
	v_mov_b32_e32 v150, v0
	v_mov_b32_e32 v152, v1
	v_mov_b32_e32 v130, v3
	v_add_f32_e32 v131, 0, v131
	v_mov_b32_e32 v134, v2
	v_pk_add_f32 v[146:147], v[150:151], v[152:153]
	v_pk_add_f32 v[130:131], v[134:135], v[130:131]
	s_nop 0
	v_pk_add_f32 v[130:131], v[146:147], v[130:131]
	s_nop 0
	v_add_f32_e32 v130, v130, v131
	ds_bpermute_b32 v131, v218, v130
	s_waitcnt lgkmcnt(0)
	v_add_f32_e32 v130, v130, v131
	ds_bpermute_b32 v131, v219, v130
	s_waitcnt lgkmcnt(0)
	v_add_f32_e32 v131, v130, v131
	v_fmamk_f32 v134, v131, 0xbc800000, v15
	v_fmamk_f32 v144, v131, 0xbc800000, v13
	v_fmamk_f32 v146, v131, 0xbc800000, v11
	v_fmamk_f32 v148, v131, 0xbc800000, v9
	v_fmamk_f32 v130, v131, 0xbc800000, v14
	v_fmamk_f32 v135, v131, 0xbc800000, v12
	v_fmamk_f32 v145, v131, 0xbc800000, v10
	v_fmamk_f32 v147, v131, 0xbc800000, v8
	v_fmamk_f32 v150, v131, 0xbc800000, v7
	v_fmamk_f32 v152, v131, 0xbc800000, v5
	v_mul_f32_e32 v144, v144, v144
	v_mul_f32_e32 v134, v134, v134
	v_mul_f32_e32 v148, v148, v148
	v_mul_f32_e32 v146, v146, v146
	v_fmamk_f32 v149, v131, 0xbc800000, v6
	v_fmamk_f32 v151, v131, 0xbc800000, v4
	v_fmamk_f32 v154, v131, 0xbc800000, v3
	v_fmamk_f32 v156, v131, 0xbc800000, v1
	v_mul_f32_e32 v152, v152, v152
	v_mul_f32_e32 v150, v150, v150
	v_fmac_f32_e32 v144, v135, v135
	v_fmac_f32_e32 v134, v130, v130
	v_fmac_f32_e32 v148, v147, v147
	v_fmac_f32_e32 v146, v145, v145
	v_fmamk_f32 v153, v131, 0xbc800000, v2
	v_fmamk_f32 v155, v131, 0xbc800000, v0
	v_mul_f32_e32 v156, v156, v156
	v_mul_f32_e32 v154, v154, v154
	v_fmac_f32_e32 v152, v151, v151
	v_fmac_f32_e32 v150, v149, v149
	v_add_f32_e32 v130, v144, v134
	v_add_f32_e32 v134, v148, v146
	v_fmac_f32_e32 v156, v155, v155
	v_fmac_f32_e32 v154, v153, v153
	v_add_f32_e32 v135, v152, v150
	v_add_f32_e32 v130, v130, v134
	v_add_f32_e32 v144, v156, v154
	v_add_f32_e32 v130, v135, v130
	v_add_f32_e32 v130, v144, v130
	ds_bpermute_b32 v134, v218, v130
	s_waitcnt lgkmcnt(0)
	v_add_f32_e32 v134, v130, v134
	ds_bpermute_b32 v135, v219, v134
	v_lshl_add_u32 v130, v200, 5, s59
	s_waitcnt vmcnt(1)
	v_cvt_f32_i32_sdwa v145, sext(v137) dst_sel:DWORD dst_unused:UNUSED_PAD src0_sel:WORD_1
	v_cvt_f32_i32_sdwa v144, sext(v137) dst_sel:DWORD dst_unused:UNUSED_PAD src0_sel:WORD_0
	v_cvt_f32_i32_sdwa v137, sext(v136) dst_sel:DWORD dst_unused:UNUSED_PAD src0_sel:WORD_1
	v_cvt_f32_i32_sdwa v136, sext(v136) dst_sel:DWORD dst_unused:UNUSED_PAD src0_sel:WORD_0
	v_cvt_f32_i32_sdwa v147, sext(v139) dst_sel:DWORD dst_unused:UNUSED_PAD src0_sel:WORD_1
	v_cvt_f32_i32_sdwa v146, sext(v139) dst_sel:DWORD dst_unused:UNUSED_PAD src0_sel:WORD_0
	v_cvt_f32_i32_sdwa v139, sext(v138) dst_sel:DWORD dst_unused:UNUSED_PAD src0_sel:WORD_1
	v_cvt_f32_i32_sdwa v138, sext(v138) dst_sel:DWORD dst_unused:UNUSED_PAD src0_sel:WORD_0
	s_waitcnt vmcnt(0)
	v_cvt_f32_i32_sdwa v149, sext(v141) dst_sel:DWORD dst_unused:UNUSED_PAD src0_sel:WORD_1
	v_cvt_f32_i32_sdwa v148, sext(v141) dst_sel:DWORD dst_unused:UNUSED_PAD src0_sel:WORD_0
	v_cvt_f32_i32_sdwa v141, sext(v140) dst_sel:DWORD dst_unused:UNUSED_PAD src0_sel:WORD_1
	v_cvt_f32_i32_sdwa v140, sext(v140) dst_sel:DWORD dst_unused:UNUSED_PAD src0_sel:WORD_0
	v_cvt_f32_i32_sdwa v151, sext(v143) dst_sel:DWORD dst_unused:UNUSED_PAD src0_sel:WORD_1
	v_cvt_f32_i32_sdwa v150, sext(v143) dst_sel:DWORD dst_unused:UNUSED_PAD src0_sel:WORD_0
	v_cvt_f32_i32_sdwa v143, sext(v142) dst_sel:DWORD dst_unused:UNUSED_PAD src0_sel:WORD_1
	v_cvt_f32_i32_sdwa v142, sext(v142) dst_sel:DWORD dst_unused:UNUSED_PAD src0_sel:WORD_0
	v_pk_mul_f32 v[136:137], v[136:137], s[24:25] op_sel_hi:[1,0]
	v_pk_mul_f32 v[144:145], v[144:145], s[24:25] op_sel_hi:[1,0]
	v_pk_mul_f32 v[138:139], v[138:139], s[24:25] op_sel_hi:[1,0]
	v_pk_mul_f32 v[146:147], v[146:147], s[24:25] op_sel_hi:[1,0]
	v_pk_mul_f32 v[140:141], v[140:141], s[24:25] op_sel_hi:[1,0]
	v_pk_mul_f32 v[148:149], v[148:149], s[24:25] op_sel_hi:[1,0]
	v_pk_mul_f32 v[142:143], v[142:143], s[24:25] op_sel_hi:[1,0]
	v_pk_mul_f32 v[150:151], v[150:151], s[24:25] op_sel_hi:[1,0]
	v_pk_fma_f32 v[126:127], v[144:145], s[26:27], v[126:127] op_sel_hi:[1,0,1]
	v_pk_fma_f32 v[124:125], v[136:137], s[26:27], v[124:125] op_sel_hi:[1,0,1]
	v_pk_fma_f32 v[122:123], v[146:147], s[26:27], v[122:123] op_sel_hi:[1,0,1]
	v_pk_fma_f32 v[120:121], v[138:139], s[26:27], v[120:121] op_sel_hi:[1,0,1]
	v_pk_fma_f32 v[118:119], v[148:149], s[26:27], v[118:119] op_sel_hi:[1,0,1]
	v_pk_fma_f32 v[116:117], v[140:141], s[26:27], v[116:117] op_sel_hi:[1,0,1]
	v_pk_fma_f32 v[114:115], v[150:151], s[26:27], v[114:115] op_sel_hi:[1,0,1]
	v_pk_fma_f32 v[112:113], v[142:143], s[26:27], v[112:113] op_sel_hi:[1,0,1]
	s_nop 0
	s_and_saveexec_b64 s[0:1], vcc
	s_cbranch_execz .LBB0_1063
	v_mul_f32_e32 v136, 0x3c800000, v131
	s_waitcnt lgkmcnt(0)
	v_add_f32_e32 v137, v134, v135
	ds_write_b64 v130, v[136:137]

	.amdhsa_kernel _Z10fwd_kernel4Args
		.amdhsa_group_segment_fixed_size 0
		.amdhsa_private_segment_fixed_size 0
		.amdhsa_kernarg_size 416
		.amdhsa_user_sgpr_count 2
		.amdhsa_user_sgpr_dispatch_ptr 0
		.amdhsa_user_sgpr_queue_ptr 0
		.amdhsa_user_sgpr_kernarg_segment_ptr 1
		.amdhsa_user_sgpr_dispatch_id 0
		.amdhsa_user_sgpr_kernarg_preload_length 0
		.amdhsa_user_sgpr_kernarg_preload_offset 0
		.amdhsa_user_sgpr_private_segment_size 0
		.amdhsa_uses_dynamic_stack 0
		.amdhsa_enable_private_segment 0
		.amdhsa_system_sgpr_workgroup_id_x 1
		.amdhsa_system_sgpr_workgroup_id_y 0
		.amdhsa_system_sgpr_workgroup_id_z 0
		.amdhsa_system_sgpr_workgroup_info 0
		.amdhsa_system_vgpr_workitem_id 0
		.amdhsa_next_free_vgpr 256
		.amdhsa_next_free_sgpr 102
		.amdhsa_accum_offset 256
		.amdhsa_reserve_vcc 1
		.amdhsa_float_round_mode_32 0
		.amdhsa_float_round_mode_16_64 0
		.amdhsa_float_denorm_mode_32 3
		.amdhsa_float_denorm_mode_16_64 3
		.amdhsa_dx10_clamp 1
		.amdhsa_ieee_mode 1
		.amdhsa_fp16_overflow 0
		.amdhsa_tg_split 0
		.amdhsa_exception_fp_ieee_invalid_op 0
		.amdhsa_exception_fp_denorm_src 0
		.amdhsa_exception_fp_ieee_div_zero 0
		.amdhsa_exception_fp_ieee_overflow 0
		.amdhsa_exception_fp_ieee_underflow 0
		.amdhsa_exception_fp_ieee_inexact 0
		.amdhsa_exception_int_div_zero 0
	.end_amdhsa_kernel

amdhsa.kernels:
  - .agpr_count:     0
    .args:
      - .offset:         0
        .size:           160
        .value_kind:     by_value
      - .offset:         160
        .size:           4
        .value_kind:     hidden_block_count_x
      - .offset:         164
        .size:           4
        .value_kind:     hidden_block_count_y
      - .offset:         168
        .size:           4
        .value_kind:     hidden_block_count_z
      - .offset:         172
        .size:           2
        .value_kind:     hidden_group_size_x
      - .offset:         174
        .size:           2
        .value_kind:     hidden_group_size_y
      - .offset:         176
        .size:           2
        .value_kind:     hidden_group_size_z
      - .offset:         178
        .size:           2
        .value_kind:     hidden_remainder_x
      - .offset:         180
        .size:           2
        .value_kind:     hidden_remainder_y
      - .offset:         182
        .size:           2
        .value_kind:     hidden_remainder_z
      - .offset:         200
        .size:           8
        .value_kind:     hidden_global_offset_x
      - .offset:         208
        .size:           8
        .value_kind:     hidden_global_offset_y
      - .offset:         216
        .size:           8
        .value_kind:     hidden_global_offset_z
      - .offset:         224
        .size:           2
        .value_kind:     hidden_grid_dims
      - .offset:         280
        .size:           4
        .value_kind:     hidden_dynamic_lds_size
    .group_segment_fixed_size: 0
    .kernarg_segment_align: 8
    .kernarg_segment_size: 416
    .language:       OpenCL C
    .language_version:
      - 2
      - 0
    .max_flat_workgroup_size: 512
    .name:           _Z10fwd_kernel4Args
    .private_segment_fixed_size: 0
    .sgpr_count:     108
    .sgpr_spill_count: 115
    .symbol:         _Z10fwd_kernel4Args.kd
    .uniform_work_group_size: 1
    .uses_dynamic_stack: false
    .vgpr_count:     256
    .vgpr_spill_count: 0
    .wavefront_size: 64
